# GEMM K-loops: MFMA blocks raised to s_setprio 3 instead of 1
# baseline (speedup 1.0000x reference)
.LBB0_208:
	ds_read_b128 v[128:131], v194
	ds_read_b128 v[132:135], v194 offset:1024
	ds_read_b128 v[136:139], v194 offset:2048
	ds_read_b128 v[140:143], v194 offset:3072
	ds_read_b128 v[144:147], v195
	ds_read_b128 v[148:151], v195 offset:1024
	ds_read_b128 v[152:155], v195 offset:2048
	ds_read_b128 v[156:159], v195 offset:3072
	s_add_u32 s8, s6, 0xfffc0080
	s_addc_u32 s9, s7, -1
	s_cmp_eq_u32 s47, 12
	s_cselect_b32 s11, s5, s9
	s_cselect_b32 s10, s14, s8
	s_cselect_b32 s9, s15, s46
	s_cselect_b32 s8, s21, s30
	v_lshl_add_u64 v[186:187], s[6:7], 0, v[174:175]
	s_add_i32 m0, s71, 0xc000
	ds_read_b128 v[182:185], v196
	ds_read_b128 v[200:203], v196 offset:1024
	ds_read_b128 v[204:207], v196 offset:2048
	ds_read_b128 v[218:221], v196 offset:3072
	ds_read_b128 v[222:225], v196 offset:4096
	ds_read_b128 v[226:229], v196 offset:5120
	ds_read_b128 v[230:233], v196 offset:6144
	ds_read_b128 v[234:237], v196 offset:7168
	global_load_lds_dwordx4 v[186:187], off
	v_lshl_add_u64 v[186:187], s[6:7], 0, v[176:177]
	s_add_i32 m0, s71, 0xe000
	s_nop 0
	global_load_lds_dwordx4 v[186:187], off
	s_waitcnt vmcnt(8)
	s_waitcnt lgkmcnt(0)
	s_barrier
	s_setprio 3
	s_waitcnt lgkmcnt(0)
	v_mfma_f32_16x16x32_bf16 v[124:127], v[128:131], v[182:185], v[124:127]
	v_mfma_f32_16x16x32_bf16 v[120:123], v[136:139], v[182:185], v[120:123]
	v_mfma_f32_16x16x32_bf16 v[108:111], v[128:131], v[204:207], v[108:111]
	v_mfma_f32_16x16x32_bf16 v[104:107], v[136:139], v[204:207], v[104:107]
	v_mfma_f32_16x16x32_bf16 v[92:95], v[128:131], v[222:225], v[92:95]
	v_mfma_f32_16x16x32_bf16 v[88:91], v[136:139], v[222:225], v[88:91]
	v_mfma_f32_16x16x32_bf16 v[76:79], v[128:131], v[230:233], v[76:79]
	v_mfma_f32_16x16x32_bf16 v[72:75], v[136:139], v[230:233], v[72:75]
	v_mfma_f32_16x16x32_bf16 v[124:127], v[132:135], v[200:203], v[124:127]
	v_mfma_f32_16x16x32_bf16 v[120:123], v[140:143], v[200:203], v[120:123]
	v_mfma_f32_16x16x32_bf16 v[108:111], v[132:135], v[218:221], v[108:111]
	v_mfma_f32_16x16x32_bf16 v[104:107], v[140:143], v[218:221], v[104:107]
	v_mfma_f32_16x16x32_bf16 v[92:95], v[132:135], v[226:229], v[92:95]
	v_mfma_f32_16x16x32_bf16 v[88:91], v[140:143], v[226:229], v[88:91]
	v_mfma_f32_16x16x32_bf16 v[76:79], v[132:135], v[234:237], v[76:79]
	v_mfma_f32_16x16x32_bf16 v[72:75], v[140:143], v[234:237], v[72:75]
	s_setprio 0
	s_setprio 3
	v_mfma_f32_16x16x32_bf16 v[116:119], v[144:147], v[182:185], v[116:119]
	v_mfma_f32_16x16x32_bf16 v[112:115], v[152:155], v[182:185], v[112:115]
	v_mfma_f32_16x16x32_bf16 v[100:103], v[144:147], v[204:207], v[100:103]
	v_mfma_f32_16x16x32_bf16 v[96:99], v[152:155], v[204:207], v[96:99]
	v_mfma_f32_16x16x32_bf16 v[84:87], v[144:147], v[222:225], v[84:87]
	v_mfma_f32_16x16x32_bf16 v[80:83], v[152:155], v[222:225], v[80:83]
	v_mfma_f32_16x16x32_bf16 v[68:71], v[144:147], v[230:233], v[68:71]
	v_mfma_f32_16x16x32_bf16 v[64:67], v[152:155], v[230:233], v[64:67]
	v_mfma_f32_16x16x32_bf16 v[116:119], v[148:151], v[200:203], v[116:119]
	v_mfma_f32_16x16x32_bf16 v[112:115], v[156:159], v[200:203], v[112:115]
	v_mfma_f32_16x16x32_bf16 v[100:103], v[148:151], v[218:221], v[100:103]
	v_mfma_f32_16x16x32_bf16 v[96:99], v[156:159], v[218:221], v[96:99]
	v_mfma_f32_16x16x32_bf16 v[84:87], v[148:151], v[226:229], v[84:87]
	v_mfma_f32_16x16x32_bf16 v[80:83], v[156:159], v[226:229], v[80:83]
	v_mfma_f32_16x16x32_bf16 v[68:71], v[148:151], v[234:237], v[68:71]
	v_mfma_f32_16x16x32_bf16 v[64:67], v[156:159], v[234:237], v[64:67]
	s_setprio 0
	s_barrier
	s_add_i32 s48, s88, s35
	v_lshl_add_u64 v[186:187], s[8:9], 0, v[160:161]
	s_mov_b32 m0, s48
	ds_read_b128 v[182:185], v196 offset:16384
	ds_read_b128 v[200:203], v196 offset:17408
	ds_read_b128 v[204:207], v196 offset:18432
	ds_read_b128 v[218:221], v196 offset:19456
	ds_read_b128 v[222:225], v196 offset:20480
	ds_read_b128 v[226:229], v196 offset:21504
	ds_read_b128 v[230:233], v196 offset:22528
	ds_read_b128 v[234:237], v196 offset:23552
	global_load_lds_dwordx4 v[186:187], off
	s_add_i32 m0, s48, 0x2000
	s_add_u32 s48, s8, 0x40000
	v_lshl_add_u64 v[208:209], s[8:9], 0, v[162:163]
	s_addc_u32 s49, s9, 0
	s_add_i32 s54, s89, s35
	global_load_lds_dwordx4 v[208:209], off
	v_lshl_add_u64 v[238:239], s[48:49], 0, v[160:161]
	s_mov_b32 m0, s54
	v_lshl_add_u64 v[240:241], s[10:11], 0, v[162:163]
	global_load_lds_dwordx4 v[238:239], off
	v_lshl_add_u64 v[238:239], s[48:49], 0, v[162:163]
	s_add_i32 m0, s54, 0x2000
	s_nop 0
	global_load_lds_dwordx4 v[238:239], off
	v_lshl_add_u64 v[238:239], s[10:11], 0, v[160:161]
	s_mov_b32 m0, s71
	s_nop 0
	global_load_lds_dwordx4 v[238:239], off
	s_mov_b32 m0, s81
	s_nop 0
	global_load_lds_dwordx4 v[240:241], off
	s_waitcnt vmcnt(8)
	s_waitcnt lgkmcnt(0)
	s_barrier
	s_setprio 3
	s_waitcnt lgkmcnt(0)
	v_mfma_f32_16x16x32_bf16 v[60:63], v[128:131], v[182:185], v[60:63]
	v_mfma_f32_16x16x32_bf16 v[56:59], v[136:139], v[182:185], v[56:59]
	v_mfma_f32_16x16x32_bf16 v[44:47], v[128:131], v[204:207], v[44:47]
	v_mfma_f32_16x16x32_bf16 v[40:43], v[136:139], v[204:207], v[40:43]
	v_mfma_f32_16x16x32_bf16 v[28:31], v[128:131], v[222:225], v[28:31]
	v_mfma_f32_16x16x32_bf16 v[24:27], v[136:139], v[222:225], v[24:27]
	v_mfma_f32_16x16x32_bf16 v[12:15], v[128:131], v[230:233], v[12:15]
	v_mfma_f32_16x16x32_bf16 v[8:11], v[136:139], v[230:233], v[8:11]
	v_mfma_f32_16x16x32_bf16 v[60:63], v[132:135], v[200:203], v[60:63]
	v_mfma_f32_16x16x32_bf16 v[56:59], v[140:143], v[200:203], v[56:59]
	v_mfma_f32_16x16x32_bf16 v[44:47], v[132:135], v[218:221], v[44:47]
	v_mfma_f32_16x16x32_bf16 v[40:43], v[140:143], v[218:221], v[40:43]
	v_mfma_f32_16x16x32_bf16 v[28:31], v[132:135], v[226:229], v[28:31]
	v_mfma_f32_16x16x32_bf16 v[24:27], v[140:143], v[226:229], v[24:27]
	v_mfma_f32_16x16x32_bf16 v[12:15], v[132:135], v[234:237], v[12:15]
	v_mfma_f32_16x16x32_bf16 v[8:11], v[140:143], v[234:237], v[8:11]
	s_setprio 0
	s_setprio 3
	v_mfma_f32_16x16x32_bf16 v[52:55], v[144:147], v[182:185], v[52:55]
	v_mfma_f32_16x16x32_bf16 v[48:51], v[152:155], v[182:185], v[48:51]
	v_mfma_f32_16x16x32_bf16 v[36:39], v[144:147], v[204:207], v[36:39]
	v_mfma_f32_16x16x32_bf16 v[32:35], v[152:155], v[204:207], v[32:35]
	v_mfma_f32_16x16x32_bf16 v[20:23], v[144:147], v[222:225], v[20:23]
	v_mfma_f32_16x16x32_bf16 v[16:19], v[152:155], v[222:225], v[16:19]
	v_mfma_f32_16x16x32_bf16 v[4:7], v[144:147], v[230:233], v[4:7]
	v_mfma_f32_16x16x32_bf16 v[0:3], v[152:155], v[230:233], v[0:3]
	v_mfma_f32_16x16x32_bf16 v[52:55], v[148:151], v[200:203], v[52:55]
	v_mfma_f32_16x16x32_bf16 v[48:51], v[156:159], v[200:203], v[48:51]
	v_mfma_f32_16x16x32_bf16 v[36:39], v[148:151], v[218:221], v[36:39]
	v_mfma_f32_16x16x32_bf16 v[32:35], v[156:159], v[218:221], v[32:35]
	v_mfma_f32_16x16x32_bf16 v[20:23], v[148:151], v[226:229], v[20:23]
	v_mfma_f32_16x16x32_bf16 v[16:19], v[156:159], v[226:229], v[16:19]
	v_mfma_f32_16x16x32_bf16 v[4:7], v[148:151], v[234:237], v[4:7]
	v_mfma_f32_16x16x32_bf16 v[0:3], v[156:159], v[234:237], v[0:3]
	s_setprio 0
	s_barrier
	s_add_i32 s48, 0, 0x18000
	s_add_i32 s49, 0, 0x1c000
	v_add_u32_e32 v140, s48, v188
	v_add_u32_e32 v156, s49, v188
	ds_read_b128 v[128:131], v140
	ds_read_b128 v[132:135], v140 offset:1024
	ds_read_b128 v[136:139], v140 offset:2048
	ds_read_b128 v[140:143], v140 offset:3072
	ds_read_b128 v[144:147], v156
	ds_read_b128 v[148:151], v156 offset:1024
	ds_read_b128 v[152:155], v156 offset:2048
	ds_read_b128 v[156:159], v156 offset:3072
	s_add_u32 s10, s10, 0x40000
	s_addc_u32 s11, s11, 0
	s_mov_b32 m0, s36
	v_lshl_add_u64 v[242:243], s[10:11], 0, v[160:161]
	ds_read_b128 v[182:185], v196 offset:32768
	ds_read_b128 v[200:203], v196 offset:33792
	ds_read_b128 v[204:207], v196 offset:34816
	ds_read_b128 v[218:221], v196 offset:35840
	ds_read_b128 v[222:225], v196 offset:36864
	ds_read_b128 v[226:229], v196 offset:37888
	ds_read_b128 v[230:233], v196 offset:38912
	ds_read_b128 v[234:237], v196 offset:39936
	global_load_lds_dwordx4 v[242:243], off
	v_lshl_add_u64 v[242:243], s[10:11], 0, v[162:163]
	s_mov_b32 m0, s37
	s_nop 0
	global_load_lds_dwordx4 v[242:243], off
	s_waitcnt vmcnt(8)
	s_waitcnt lgkmcnt(0)
	s_barrier
	s_setprio 3
	s_waitcnt lgkmcnt(0)
	v_mfma_f32_16x16x32_bf16 v[124:127], v[128:131], v[182:185], v[124:127]
	v_mfma_f32_16x16x32_bf16 v[120:123], v[136:139], v[182:185], v[120:123]
	v_mfma_f32_16x16x32_bf16 v[108:111], v[128:131], v[204:207], v[108:111]
	v_mfma_f32_16x16x32_bf16 v[104:107], v[136:139], v[204:207], v[104:107]
	v_mfma_f32_16x16x32_bf16 v[92:95], v[128:131], v[222:225], v[92:95]
	v_mfma_f32_16x16x32_bf16 v[88:91], v[136:139], v[222:225], v[88:91]
	v_mfma_f32_16x16x32_bf16 v[76:79], v[128:131], v[230:233], v[76:79]
	v_mfma_f32_16x16x32_bf16 v[72:75], v[136:139], v[230:233], v[72:75]
	v_mfma_f32_16x16x32_bf16 v[124:127], v[132:135], v[200:203], v[124:127]
	v_mfma_f32_16x16x32_bf16 v[120:123], v[140:143], v[200:203], v[120:123]
	v_mfma_f32_16x16x32_bf16 v[108:111], v[132:135], v[218:221], v[108:111]
	v_mfma_f32_16x16x32_bf16 v[104:107], v[140:143], v[218:221], v[104:107]
	v_mfma_f32_16x16x32_bf16 v[92:95], v[132:135], v[226:229], v[92:95]
	v_mfma_f32_16x16x32_bf16 v[88:91], v[140:143], v[226:229], v[88:91]
	v_mfma_f32_16x16x32_bf16 v[76:79], v[132:135], v[234:237], v[76:79]
	v_mfma_f32_16x16x32_bf16 v[72:75], v[140:143], v[234:237], v[72:75]
	s_setprio 0
	s_setprio 3
	v_mfma_f32_16x16x32_bf16 v[116:119], v[144:147], v[182:185], v[116:119]
	v_mfma_f32_16x16x32_bf16 v[112:115], v[152:155], v[182:185], v[112:115]
	v_mfma_f32_16x16x32_bf16 v[100:103], v[144:147], v[204:207], v[100:103]
	v_mfma_f32_16x16x32_bf16 v[96:99], v[152:155], v[204:207], v[96:99]
	v_mfma_f32_16x16x32_bf16 v[84:87], v[144:147], v[222:225], v[84:87]
	v_mfma_f32_16x16x32_bf16 v[80:83], v[152:155], v[222:225], v[80:83]
	v_mfma_f32_16x16x32_bf16 v[68:71], v[144:147], v[230:233], v[68:71]
	v_mfma_f32_16x16x32_bf16 v[64:67], v[152:155], v[230:233], v[64:67]
	v_mfma_f32_16x16x32_bf16 v[116:119], v[148:151], v[200:203], v[116:119]
	v_mfma_f32_16x16x32_bf16 v[112:115], v[156:159], v[200:203], v[112:115]
	v_mfma_f32_16x16x32_bf16 v[100:103], v[148:151], v[218:221], v[100:103]
	v_mfma_f32_16x16x32_bf16 v[96:99], v[156:159], v[218:221], v[96:99]
	v_mfma_f32_16x16x32_bf16 v[84:87], v[148:151], v[226:229], v[84:87]
	v_mfma_f32_16x16x32_bf16 v[80:83], v[156:159], v[226:229], v[80:83]
	v_mfma_f32_16x16x32_bf16 v[68:71], v[148:151], v[234:237], v[68:71]
	v_mfma_f32_16x16x32_bf16 v[64:67], v[156:159], v[234:237], v[64:67]
	s_setprio 0
	s_barrier
	s_add_i32 s10, s48, s35
	v_lshl_add_u64 v[186:187], v[186:187], 0, s[50:51]
	s_mov_b32 m0, s10
	ds_read_b128 v[182:185], v196 offset:49152
	ds_read_b128 v[200:203], v196 offset:50176
	ds_read_b128 v[204:207], v196 offset:51200
	ds_read_b128 v[218:221], v196 offset:52224
	ds_read_b128 v[222:225], v196 offset:53248
	ds_read_b128 v[226:229], v196 offset:54272
	ds_read_b128 v[230:233], v196 offset:55296
	ds_read_b128 v[234:237], v196 offset:56320
	global_load_lds_dwordx4 v[186:187], off
	s_add_i32 m0, s10, 0x2000
	s_add_u32 s8, s8, 0x40080
	v_lshl_add_u64 v[186:187], v[208:209], 0, s[50:51]
	s_addc_u32 s9, s9, 0
	s_add_i32 s10, s49, s35
	global_load_lds_dwordx4 v[186:187], off
	v_lshl_add_u64 v[186:187], s[8:9], 0, v[160:161]
	s_mov_b32 m0, s10
	s_nop 0
	global_load_lds_dwordx4 v[186:187], off
	v_lshl_add_u64 v[186:187], s[8:9], 0, v[162:163]
	s_add_i32 m0, s10, 0x2000
	s_nop 0
	global_load_lds_dwordx4 v[186:187], off
	v_lshl_add_u64 v[186:187], v[238:239], 0, s[50:51]
	s_mov_b32 m0, s39
	s_nop 0
	global_load_lds_dwordx4 v[186:187], off
	v_lshl_add_u64 v[186:187], v[240:241], 0, s[50:51]
	s_mov_b32 m0, s40
	s_nop 0
	global_load_lds_dwordx4 v[186:187], off
	s_waitcnt vmcnt(8)
	s_waitcnt lgkmcnt(0)
	s_barrier
	s_setprio 3
	s_waitcnt lgkmcnt(0)
	v_mfma_f32_16x16x32_bf16 v[60:63], v[128:131], v[182:185], v[60:63]
	v_mfma_f32_16x16x32_bf16 v[56:59], v[136:139], v[182:185], v[56:59]
	v_mfma_f32_16x16x32_bf16 v[44:47], v[128:131], v[204:207], v[44:47]
	v_mfma_f32_16x16x32_bf16 v[40:43], v[136:139], v[204:207], v[40:43]
	v_mfma_f32_16x16x32_bf16 v[28:31], v[128:131], v[222:225], v[28:31]
	v_mfma_f32_16x16x32_bf16 v[24:27], v[136:139], v[222:225], v[24:27]
	v_mfma_f32_16x16x32_bf16 v[12:15], v[128:131], v[230:233], v[12:15]
	v_mfma_f32_16x16x32_bf16 v[8:11], v[136:139], v[230:233], v[8:11]
	v_mfma_f32_16x16x32_bf16 v[60:63], v[132:135], v[200:203], v[60:63]
	v_mfma_f32_16x16x32_bf16 v[56:59], v[140:143], v[200:203], v[56:59]
	v_mfma_f32_16x16x32_bf16 v[44:47], v[132:135], v[218:221], v[44:47]
	v_mfma_f32_16x16x32_bf16 v[40:43], v[140:143], v[218:221], v[40:43]
	v_mfma_f32_16x16x32_bf16 v[28:31], v[132:135], v[226:229], v[28:31]
	v_mfma_f32_16x16x32_bf16 v[24:27], v[140:143], v[226:229], v[24:27]
	v_mfma_f32_16x16x32_bf16 v[12:15], v[132:135], v[234:237], v[12:15]
	v_mfma_f32_16x16x32_bf16 v[8:11], v[140:143], v[234:237], v[8:11]
	s_setprio 0
	s_setprio 3
	v_mfma_f32_16x16x32_bf16 v[52:55], v[144:147], v[182:185], v[52:55]
	v_mfma_f32_16x16x32_bf16 v[48:51], v[152:155], v[182:185], v[48:51]
	v_mfma_f32_16x16x32_bf16 v[36:39], v[144:147], v[204:207], v[36:39]
	v_mfma_f32_16x16x32_bf16 v[32:35], v[152:155], v[204:207], v[32:35]
	v_mfma_f32_16x16x32_bf16 v[20:23], v[144:147], v[222:225], v[20:23]
	v_mfma_f32_16x16x32_bf16 v[16:19], v[152:155], v[222:225], v[16:19]
	v_mfma_f32_16x16x32_bf16 v[4:7], v[144:147], v[230:233], v[4:7]
	v_mfma_f32_16x16x32_bf16 v[0:3], v[152:155], v[230:233], v[0:3]
	v_mfma_f32_16x16x32_bf16 v[52:55], v[148:151], v[200:203], v[52:55]
	v_mfma_f32_16x16x32_bf16 v[48:51], v[156:159], v[200:203], v[48:51]
	v_mfma_f32_16x16x32_bf16 v[36:39], v[148:151], v[218:221], v[36:39]
	v_mfma_f32_16x16x32_bf16 v[32:35], v[156:159], v[218:221], v[32:35]
	v_mfma_f32_16x16x32_bf16 v[20:23], v[148:151], v[226:229], v[20:23]
	v_mfma_f32_16x16x32_bf16 v[16:19], v[156:159], v[226:229], v[16:19]
	v_mfma_f32_16x16x32_bf16 v[4:7], v[148:151], v[234:237], v[4:7]
	v_mfma_f32_16x16x32_bf16 v[0:3], v[156:159], v[234:237], v[0:3]
	s_setprio 0
	s_barrier
	s_add_i32 s47, s47, 2
	s_add_u32 s6, s6, 0x100
	s_addc_u32 s7, s7, 0
	s_add_u32 s30, s30, 0x100
	s_addc_u32 s46, s46, 0
	s_cmp_gt_u32 s47, 13
	s_cbranch_scc0 .LBB0_208
	s_and_b64 vcc, exec, s[82:83]
	s_cbranch_vccz .LBB0_211
	s_barrier

.LBB0_702:
	s_add_u32 s20, s46, s48
	s_addc_u32 s21, s47, s49
	s_add_u32 s20, s20, 0x100
	s_addc_u32 s21, s21, 0
	s_add_u32 s72, s69, s48
	s_addc_u32 s73, s70, s49
	s_add_i32 s74, 0, 0x10000
	v_add_u32_e32 v172, s74, v162
	v_add_u32_e32 v188, s62, v162
	ds_read_b128 v[128:131], v172
	ds_read_b128 v[132:135], v172 offset:1024
	ds_read_b128 v[168:171], v172 offset:2048
	ds_read_b128 v[172:175], v172 offset:3072
	ds_read_b128 v[176:179], v188
	ds_read_b128 v[180:183], v188 offset:1024
	ds_read_b128 v[184:187], v188 offset:2048
	ds_read_b128 v[188:191], v188 offset:3072
	s_cmpk_eq_i32 s48, 0x700
	s_cselect_b32 s51, s43, s21
	s_cselect_b32 s50, s42, s20
	s_cselect_b32 s21, s41, s73
	s_cselect_b32 s20, s68, s72
	v_lshl_add_u64 v[208:209], v[156:157], 0, s[48:49]
	s_add_i32 m0, s53, 0xc000
	ds_read_b128 v[192:195], v165
	ds_read_b128 v[196:199], v165 offset:1024
	ds_read_b128 v[200:203], v165 offset:2048
	ds_read_b128 v[204:207], v165 offset:3072
	ds_read_b128 v[218:221], v165 offset:4096
	ds_read_b128 v[222:225], v165 offset:5120
	ds_read_b128 v[226:229], v165 offset:6144
	ds_read_b128 v[230:233], v165 offset:7168
	global_load_lds_dwordx4 v[208:209], off
	v_lshl_add_u64 v[208:209], v[158:159], 0, s[48:49]
	s_add_i32 m0, s53, 0xe000
	s_nop 0
	global_load_lds_dwordx4 v[208:209], off
	s_waitcnt vmcnt(8)
	s_waitcnt lgkmcnt(0)
	s_barrier
	s_setprio 3
	s_waitcnt lgkmcnt(0)
	v_mfma_f32_16x16x32_bf16 v[124:127], v[128:131], v[192:195], v[124:127]
	v_mfma_f32_16x16x32_bf16 v[120:123], v[168:171], v[192:195], v[120:123]
	v_mfma_f32_16x16x32_bf16 v[108:111], v[128:131], v[200:203], v[108:111]
	v_mfma_f32_16x16x32_bf16 v[104:107], v[168:171], v[200:203], v[104:107]
	v_mfma_f32_16x16x32_bf16 v[92:95], v[128:131], v[218:221], v[92:95]
	v_mfma_f32_16x16x32_bf16 v[88:91], v[168:171], v[218:221], v[88:91]
	v_mfma_f32_16x16x32_bf16 v[76:79], v[128:131], v[226:229], v[76:79]
	v_mfma_f32_16x16x32_bf16 v[72:75], v[168:171], v[226:229], v[72:75]
	v_mfma_f32_16x16x32_bf16 v[124:127], v[132:135], v[196:199], v[124:127]
	v_mfma_f32_16x16x32_bf16 v[120:123], v[172:175], v[196:199], v[120:123]
	v_mfma_f32_16x16x32_bf16 v[108:111], v[132:135], v[204:207], v[108:111]
	v_mfma_f32_16x16x32_bf16 v[104:107], v[172:175], v[204:207], v[104:107]
	v_mfma_f32_16x16x32_bf16 v[92:95], v[132:135], v[222:225], v[92:95]
	v_mfma_f32_16x16x32_bf16 v[88:91], v[172:175], v[222:225], v[88:91]
	v_mfma_f32_16x16x32_bf16 v[76:79], v[132:135], v[230:233], v[76:79]
	v_mfma_f32_16x16x32_bf16 v[72:75], v[172:175], v[230:233], v[72:75]
	s_setprio 0
	s_setprio 3
	v_mfma_f32_16x16x32_bf16 v[116:119], v[176:179], v[192:195], v[116:119]
	v_mfma_f32_16x16x32_bf16 v[112:115], v[184:187], v[192:195], v[112:115]
	v_mfma_f32_16x16x32_bf16 v[100:103], v[176:179], v[200:203], v[100:103]
	v_mfma_f32_16x16x32_bf16 v[96:99], v[184:187], v[200:203], v[96:99]
	v_mfma_f32_16x16x32_bf16 v[84:87], v[176:179], v[218:221], v[84:87]
	v_mfma_f32_16x16x32_bf16 v[80:83], v[184:187], v[218:221], v[80:83]
	v_mfma_f32_16x16x32_bf16 v[68:71], v[176:179], v[226:229], v[68:71]
	v_mfma_f32_16x16x32_bf16 v[64:67], v[184:187], v[226:229], v[64:67]
	v_mfma_f32_16x16x32_bf16 v[116:119], v[180:183], v[196:199], v[116:119]
	v_mfma_f32_16x16x32_bf16 v[112:115], v[188:191], v[196:199], v[112:115]
	v_mfma_f32_16x16x32_bf16 v[100:103], v[180:183], v[204:207], v[100:103]
	v_mfma_f32_16x16x32_bf16 v[96:99], v[188:191], v[204:207], v[96:99]
	v_mfma_f32_16x16x32_bf16 v[84:87], v[180:183], v[222:225], v[84:87]
	v_mfma_f32_16x16x32_bf16 v[80:83], v[188:191], v[222:225], v[80:83]
	v_mfma_f32_16x16x32_bf16 v[68:71], v[180:183], v[230:233], v[68:71]
	v_mfma_f32_16x16x32_bf16 v[64:67], v[188:191], v[230:233], v[64:67]
	s_setprio 0
	s_barrier
	s_add_i32 s72, s74, s3
	v_lshl_add_u64 v[208:209], s[20:21], 0, v[140:141]
	s_mov_b32 m0, s72
	ds_read_b128 v[192:195], v165 offset:16384
	ds_read_b128 v[196:199], v165 offset:17408
	ds_read_b128 v[200:203], v165 offset:18432
	ds_read_b128 v[204:207], v165 offset:19456
	ds_read_b128 v[218:221], v165 offset:20480
	ds_read_b128 v[222:225], v165 offset:21504
	ds_read_b128 v[226:229], v165 offset:22528
	ds_read_b128 v[230:233], v165 offset:23552
	global_load_lds_dwordx4 v[208:209], off
	s_add_i32 m0, s72, 0x2000
	s_add_u32 s72, s20, 0x40000
	v_lshl_add_u64 v[234:235], s[20:21], 0, v[136:137]
	s_addc_u32 s73, s21, 0
	s_add_i32 s74, s62, s3
	global_load_lds_dwordx4 v[234:235], off
	v_lshl_add_u64 v[236:237], s[72:73], 0, v[140:141]
	s_mov_b32 m0, s74
	v_lshl_add_u64 v[238:239], s[50:51], 0, v[138:139]
	global_load_lds_dwordx4 v[236:237], off
	v_lshl_add_u64 v[236:237], s[72:73], 0, v[136:137]
	s_add_i32 m0, s74, 0x2000
	s_nop 0
	global_load_lds_dwordx4 v[236:237], off
	v_lshl_add_u64 v[236:237], s[50:51], 0, v[142:143]
	s_mov_b32 m0, s53
	s_nop 0
	global_load_lds_dwordx4 v[236:237], off
	s_mov_b32 m0, s54
	s_nop 0
	global_load_lds_dwordx4 v[238:239], off
	s_waitcnt vmcnt(8)
	s_waitcnt lgkmcnt(0)
	s_barrier
	s_setprio 3
	s_waitcnt lgkmcnt(0)
	v_mfma_f32_16x16x32_bf16 v[60:63], v[128:131], v[192:195], v[60:63]
	v_mfma_f32_16x16x32_bf16 v[56:59], v[168:171], v[192:195], v[56:59]
	v_mfma_f32_16x16x32_bf16 v[44:47], v[128:131], v[200:203], v[44:47]
	v_mfma_f32_16x16x32_bf16 v[40:43], v[168:171], v[200:203], v[40:43]
	v_mfma_f32_16x16x32_bf16 v[28:31], v[128:131], v[218:221], v[28:31]
	v_mfma_f32_16x16x32_bf16 v[24:27], v[168:171], v[218:221], v[24:27]
	v_mfma_f32_16x16x32_bf16 v[12:15], v[128:131], v[226:229], v[12:15]
	v_mfma_f32_16x16x32_bf16 v[8:11], v[168:171], v[226:229], v[8:11]
	v_mfma_f32_16x16x32_bf16 v[60:63], v[132:135], v[196:199], v[60:63]
	v_mfma_f32_16x16x32_bf16 v[56:59], v[172:175], v[196:199], v[56:59]
	v_mfma_f32_16x16x32_bf16 v[44:47], v[132:135], v[204:207], v[44:47]
	v_mfma_f32_16x16x32_bf16 v[40:43], v[172:175], v[204:207], v[40:43]
	v_mfma_f32_16x16x32_bf16 v[28:31], v[132:135], v[222:225], v[28:31]
	v_mfma_f32_16x16x32_bf16 v[24:27], v[172:175], v[222:225], v[24:27]
	v_mfma_f32_16x16x32_bf16 v[12:15], v[132:135], v[230:233], v[12:15]
	v_mfma_f32_16x16x32_bf16 v[8:11], v[172:175], v[230:233], v[8:11]
	s_setprio 0
	s_setprio 3
	v_mfma_f32_16x16x32_bf16 v[52:55], v[176:179], v[192:195], v[52:55]
	v_mfma_f32_16x16x32_bf16 v[48:51], v[184:187], v[192:195], v[48:51]
	v_mfma_f32_16x16x32_bf16 v[36:39], v[176:179], v[200:203], v[36:39]
	v_mfma_f32_16x16x32_bf16 v[32:35], v[184:187], v[200:203], v[32:35]
	v_mfma_f32_16x16x32_bf16 v[20:23], v[176:179], v[218:221], v[20:23]
	v_mfma_f32_16x16x32_bf16 v[16:19], v[184:187], v[218:221], v[16:19]
	v_mfma_f32_16x16x32_bf16 v[4:7], v[176:179], v[226:229], v[4:7]
	v_mfma_f32_16x16x32_bf16 v[0:3], v[184:187], v[226:229], v[0:3]
	v_mfma_f32_16x16x32_bf16 v[52:55], v[180:183], v[196:199], v[52:55]
	v_mfma_f32_16x16x32_bf16 v[48:51], v[188:191], v[196:199], v[48:51]
	v_mfma_f32_16x16x32_bf16 v[36:39], v[180:183], v[204:207], v[36:39]
	v_mfma_f32_16x16x32_bf16 v[32:35], v[188:191], v[204:207], v[32:35]
	v_mfma_f32_16x16x32_bf16 v[20:23], v[180:183], v[222:225], v[20:23]
	v_mfma_f32_16x16x32_bf16 v[16:19], v[188:191], v[222:225], v[16:19]
	v_mfma_f32_16x16x32_bf16 v[4:7], v[180:183], v[230:233], v[4:7]
	v_mfma_f32_16x16x32_bf16 v[0:3], v[188:191], v[230:233], v[0:3]
	s_setprio 0
	s_barrier
	s_add_i32 s72, 0, 0x18000
	s_add_i32 s73, 0, 0x1c000
	v_add_u32_e32 v172, s72, v162
	v_add_u32_e32 v188, s73, v162
	ds_read_b128 v[128:131], v172
	ds_read_b128 v[132:135], v172 offset:1024
	ds_read_b128 v[168:171], v172 offset:2048
	ds_read_b128 v[172:175], v172 offset:3072
	ds_read_b128 v[176:179], v188
	ds_read_b128 v[180:183], v188 offset:1024
	ds_read_b128 v[184:187], v188 offset:2048
	ds_read_b128 v[188:191], v188 offset:3072
	s_add_u32 s50, s50, 0x60000
	s_addc_u32 s51, s51, 0
	s_mov_b32 m0, s55
	v_lshl_add_u64 v[240:241], s[50:51], 0, v[142:143]
	ds_read_b128 v[192:195], v165 offset:32768
	ds_read_b128 v[196:199], v165 offset:33792
	ds_read_b128 v[200:203], v165 offset:34816
	ds_read_b128 v[204:207], v165 offset:35840
	ds_read_b128 v[218:221], v165 offset:36864
	ds_read_b128 v[222:225], v165 offset:37888
	ds_read_b128 v[226:229], v165 offset:38912
	ds_read_b128 v[230:233], v165 offset:39936
	global_load_lds_dwordx4 v[240:241], off
	v_lshl_add_u64 v[240:241], s[50:51], 0, v[138:139]
	s_mov_b32 m0, s56
	s_nop 0
	global_load_lds_dwordx4 v[240:241], off
	s_waitcnt vmcnt(8)
	s_waitcnt lgkmcnt(0)
	s_barrier
	s_setprio 3
	s_waitcnt lgkmcnt(0)
	v_mfma_f32_16x16x32_bf16 v[124:127], v[128:131], v[192:195], v[124:127]
	v_mfma_f32_16x16x32_bf16 v[120:123], v[168:171], v[192:195], v[120:123]
	v_mfma_f32_16x16x32_bf16 v[108:111], v[128:131], v[200:203], v[108:111]
	v_mfma_f32_16x16x32_bf16 v[104:107], v[168:171], v[200:203], v[104:107]
	v_mfma_f32_16x16x32_bf16 v[92:95], v[128:131], v[218:221], v[92:95]
	v_mfma_f32_16x16x32_bf16 v[88:91], v[168:171], v[218:221], v[88:91]
	v_mfma_f32_16x16x32_bf16 v[76:79], v[128:131], v[226:229], v[76:79]
	v_mfma_f32_16x16x32_bf16 v[72:75], v[168:171], v[226:229], v[72:75]
	v_mfma_f32_16x16x32_bf16 v[124:127], v[132:135], v[196:199], v[124:127]
	v_mfma_f32_16x16x32_bf16 v[120:123], v[172:175], v[196:199], v[120:123]
	v_mfma_f32_16x16x32_bf16 v[108:111], v[132:135], v[204:207], v[108:111]
	v_mfma_f32_16x16x32_bf16 v[104:107], v[172:175], v[204:207], v[104:107]
	v_mfma_f32_16x16x32_bf16 v[92:95], v[132:135], v[222:225], v[92:95]
	v_mfma_f32_16x16x32_bf16 v[88:91], v[172:175], v[222:225], v[88:91]
	v_mfma_f32_16x16x32_bf16 v[76:79], v[132:135], v[230:233], v[76:79]
	v_mfma_f32_16x16x32_bf16 v[72:75], v[172:175], v[230:233], v[72:75]
	s_setprio 0
	s_setprio 3
	v_mfma_f32_16x16x32_bf16 v[116:119], v[176:179], v[192:195], v[116:119]
	v_mfma_f32_16x16x32_bf16 v[112:115], v[184:187], v[192:195], v[112:115]
	v_mfma_f32_16x16x32_bf16 v[100:103], v[176:179], v[200:203], v[100:103]
	v_mfma_f32_16x16x32_bf16 v[96:99], v[184:187], v[200:203], v[96:99]
	v_mfma_f32_16x16x32_bf16 v[84:87], v[176:179], v[218:221], v[84:87]
	v_mfma_f32_16x16x32_bf16 v[80:83], v[184:187], v[218:221], v[80:83]
	v_mfma_f32_16x16x32_bf16 v[68:71], v[176:179], v[226:229], v[68:71]
	v_mfma_f32_16x16x32_bf16 v[64:67], v[184:187], v[226:229], v[64:67]
	v_mfma_f32_16x16x32_bf16 v[116:119], v[180:183], v[196:199], v[116:119]
	v_mfma_f32_16x16x32_bf16 v[112:115], v[188:191], v[196:199], v[112:115]
	v_mfma_f32_16x16x32_bf16 v[100:103], v[180:183], v[204:207], v[100:103]
	v_mfma_f32_16x16x32_bf16 v[96:99], v[188:191], v[204:207], v[96:99]
	v_mfma_f32_16x16x32_bf16 v[84:87], v[180:183], v[222:225], v[84:87]
	v_mfma_f32_16x16x32_bf16 v[80:83], v[188:191], v[222:225], v[80:83]
	v_mfma_f32_16x16x32_bf16 v[68:71], v[180:183], v[230:233], v[68:71]
	v_mfma_f32_16x16x32_bf16 v[64:67], v[188:191], v[230:233], v[64:67]
	s_setprio 0
	s_barrier
	s_add_i32 s50, s72, s3
	v_lshl_add_u64 v[208:209], v[208:209], 0, s[12:13]
	s_mov_b32 m0, s50
	ds_read_b128 v[192:195], v165 offset:49152
	ds_read_b128 v[196:199], v165 offset:50176
	ds_read_b128 v[200:203], v165 offset:51200
	ds_read_b128 v[204:207], v165 offset:52224
	ds_read_b128 v[218:221], v165 offset:53248
	ds_read_b128 v[222:225], v165 offset:54272
	ds_read_b128 v[226:229], v165 offset:55296
	ds_read_b128 v[230:233], v165 offset:56320
	global_load_lds_dwordx4 v[208:209], off
	s_add_i32 m0, s50, 0x2000
	s_add_u32 s20, s20, 0x40080
	v_lshl_add_u64 v[208:209], v[234:235], 0, s[12:13]
	s_addc_u32 s21, s21, 0
	s_add_i32 s50, s73, s3
	global_load_lds_dwordx4 v[208:209], off
	v_lshl_add_u64 v[208:209], s[20:21], 0, v[140:141]
	s_mov_b32 m0, s50
	s_nop 0
	global_load_lds_dwordx4 v[208:209], off
	v_lshl_add_u64 v[208:209], s[20:21], 0, v[136:137]
	s_add_i32 m0, s50, 0x2000
	s_nop 0
	global_load_lds_dwordx4 v[208:209], off
	v_lshl_add_u64 v[208:209], v[236:237], 0, s[12:13]
	s_mov_b32 m0, s59
	s_nop 0
	global_load_lds_dwordx4 v[208:209], off
	v_lshl_add_u64 v[208:209], v[238:239], 0, s[12:13]
	s_mov_b32 m0, s60
	s_nop 0
	global_load_lds_dwordx4 v[208:209], off
	s_waitcnt vmcnt(8)
	s_waitcnt lgkmcnt(0)
	s_barrier
	s_setprio 3
	s_waitcnt lgkmcnt(0)
	v_mfma_f32_16x16x32_bf16 v[60:63], v[128:131], v[192:195], v[60:63]
	v_mfma_f32_16x16x32_bf16 v[56:59], v[168:171], v[192:195], v[56:59]
	v_mfma_f32_16x16x32_bf16 v[44:47], v[128:131], v[200:203], v[44:47]
	v_mfma_f32_16x16x32_bf16 v[40:43], v[168:171], v[200:203], v[40:43]
	v_mfma_f32_16x16x32_bf16 v[28:31], v[128:131], v[218:221], v[28:31]
	v_mfma_f32_16x16x32_bf16 v[24:27], v[168:171], v[218:221], v[24:27]
	v_mfma_f32_16x16x32_bf16 v[12:15], v[128:131], v[226:229], v[12:15]
	v_mfma_f32_16x16x32_bf16 v[8:11], v[168:171], v[226:229], v[8:11]
	v_mfma_f32_16x16x32_bf16 v[60:63], v[132:135], v[196:199], v[60:63]
	v_mfma_f32_16x16x32_bf16 v[56:59], v[172:175], v[196:199], v[56:59]
	v_mfma_f32_16x16x32_bf16 v[44:47], v[132:135], v[204:207], v[44:47]
	v_mfma_f32_16x16x32_bf16 v[40:43], v[172:175], v[204:207], v[40:43]
	v_mfma_f32_16x16x32_bf16 v[28:31], v[132:135], v[222:225], v[28:31]
	v_mfma_f32_16x16x32_bf16 v[24:27], v[172:175], v[222:225], v[24:27]
	v_mfma_f32_16x16x32_bf16 v[12:15], v[132:135], v[230:233], v[12:15]
	v_mfma_f32_16x16x32_bf16 v[8:11], v[172:175], v[230:233], v[8:11]
	s_setprio 0
	s_setprio 3
	v_mfma_f32_16x16x32_bf16 v[52:55], v[176:179], v[192:195], v[52:55]
	v_mfma_f32_16x16x32_bf16 v[48:51], v[184:187], v[192:195], v[48:51]
	v_mfma_f32_16x16x32_bf16 v[36:39], v[176:179], v[200:203], v[36:39]
	v_mfma_f32_16x16x32_bf16 v[32:35], v[184:187], v[200:203], v[32:35]
	v_mfma_f32_16x16x32_bf16 v[20:23], v[176:179], v[218:221], v[20:23]
	v_mfma_f32_16x16x32_bf16 v[16:19], v[184:187], v[218:221], v[16:19]
	v_mfma_f32_16x16x32_bf16 v[4:7], v[176:179], v[226:229], v[4:7]
	v_mfma_f32_16x16x32_bf16 v[0:3], v[184:187], v[226:229], v[0:3]
	v_mfma_f32_16x16x32_bf16 v[52:55], v[180:183], v[196:199], v[52:55]
	v_mfma_f32_16x16x32_bf16 v[48:51], v[188:191], v[196:199], v[48:51]
	v_mfma_f32_16x16x32_bf16 v[36:39], v[180:183], v[204:207], v[36:39]
	v_mfma_f32_16x16x32_bf16 v[32:35], v[188:191], v[204:207], v[32:35]
	v_mfma_f32_16x16x32_bf16 v[20:23], v[180:183], v[222:225], v[20:23]
	v_mfma_f32_16x16x32_bf16 v[16:19], v[188:191], v[222:225], v[16:19]
	v_mfma_f32_16x16x32_bf16 v[4:7], v[180:183], v[230:233], v[4:7]
	v_mfma_f32_16x16x32_bf16 v[0:3], v[188:191], v[230:233], v[0:3]
	s_setprio 0
	s_barrier
	s_add_i32 s71, s71, 2
	s_add_u32 s48, s48, 0x100
	s_addc_u32 s49, s49, 0
	s_cmp_gt_u32 s71, 13
	s_cbranch_scc1 .LBB0_705

.LBB0_771:
	ds_read_b128 v[32:35], v162
	ds_read_b128 v[36:39], v162 offset:1024
	ds_read_b128 v[40:43], v162 offset:2048
	ds_read_b128 v[44:47], v162 offset:3072
	ds_read_b128 v[168:171], v163
	ds_read_b128 v[172:175], v163 offset:1024
	ds_read_b128 v[176:179], v163 offset:2048
	ds_read_b128 v[180:183], v163 offset:3072
	s_add_u32 s42, s40, 0xfffc0080
	s_addc_u32 s43, s41, -1
	s_cmp_eq_u32 s73, 12
	s_cselect_b32 s45, s31, s43
	s_cselect_b32 s44, s69, s42
	s_cselect_b32 s43, s29, s72
	s_cselect_b32 s42, s70, s71
	v_lshl_add_u64 v[158:159], s[40:41], 0, v[150:151]
	s_add_i32 m0, s21, 0xc000
	ds_read_b128 v[184:187], v164
	ds_read_b128 v[188:191], v164 offset:1024
	ds_read_b128 v[192:195], v164 offset:2048
	ds_read_b128 v[196:199], v164 offset:3072
	ds_read_b128 v[200:203], v164 offset:4096
	ds_read_b128 v[204:207], v164 offset:5120
	ds_read_b128 v[218:221], v164 offset:6144
	ds_read_b128 v[222:225], v164 offset:7168
	global_load_lds_dwordx4 v[158:159], off
	v_lshl_add_u64 v[158:159], s[40:41], 0, v[152:153]
	s_add_i32 m0, s21, 0xe000
	s_nop 0
	global_load_lds_dwordx4 v[158:159], off
	s_waitcnt vmcnt(8)
	s_waitcnt lgkmcnt(0)
	s_barrier
	s_setprio 3
	s_waitcnt lgkmcnt(0)
	v_mfma_f32_16x16x32_bf16 v[140:143], v[32:35], v[184:187], v[140:143]
	v_mfma_f32_16x16x32_bf16 v[136:139], v[40:43], v[184:187], v[136:139]
	v_mfma_f32_16x16x32_bf16 v[124:127], v[32:35], v[192:195], v[124:127]
	v_mfma_f32_16x16x32_bf16 v[120:123], v[40:43], v[192:195], v[120:123]
	v_mfma_f32_16x16x32_bf16 v[108:111], v[32:35], v[200:203], v[108:111]
	v_mfma_f32_16x16x32_bf16 v[104:107], v[40:43], v[200:203], v[104:107]
	v_mfma_f32_16x16x32_bf16 v[92:95], v[32:35], v[218:221], v[92:95]
	v_mfma_f32_16x16x32_bf16 v[88:91], v[40:43], v[218:221], v[88:91]
	v_mfma_f32_16x16x32_bf16 v[140:143], v[36:39], v[188:191], v[140:143]
	v_mfma_f32_16x16x32_bf16 v[136:139], v[44:47], v[188:191], v[136:139]
	v_mfma_f32_16x16x32_bf16 v[124:127], v[36:39], v[196:199], v[124:127]
	v_mfma_f32_16x16x32_bf16 v[120:123], v[44:47], v[196:199], v[120:123]
	v_mfma_f32_16x16x32_bf16 v[108:111], v[36:39], v[204:207], v[108:111]
	v_mfma_f32_16x16x32_bf16 v[104:107], v[44:47], v[204:207], v[104:107]
	v_mfma_f32_16x16x32_bf16 v[92:95], v[36:39], v[222:225], v[92:95]
	v_mfma_f32_16x16x32_bf16 v[88:91], v[44:47], v[222:225], v[88:91]
	s_setprio 0
	s_setprio 3
	v_mfma_f32_16x16x32_bf16 v[132:135], v[168:171], v[184:187], v[132:135]
	v_mfma_f32_16x16x32_bf16 v[128:131], v[176:179], v[184:187], v[128:131]
	v_mfma_f32_16x16x32_bf16 v[116:119], v[168:171], v[192:195], v[116:119]
	v_mfma_f32_16x16x32_bf16 v[112:115], v[176:179], v[192:195], v[112:115]
	v_mfma_f32_16x16x32_bf16 v[100:103], v[168:171], v[200:203], v[100:103]
	v_mfma_f32_16x16x32_bf16 v[96:99], v[176:179], v[200:203], v[96:99]
	v_mfma_f32_16x16x32_bf16 v[84:87], v[168:171], v[218:221], v[84:87]
	v_mfma_f32_16x16x32_bf16 v[80:83], v[176:179], v[218:221], v[80:83]
	v_mfma_f32_16x16x32_bf16 v[132:135], v[172:175], v[188:191], v[132:135]
	v_mfma_f32_16x16x32_bf16 v[128:131], v[180:183], v[188:191], v[128:131]
	v_mfma_f32_16x16x32_bf16 v[116:119], v[172:175], v[196:199], v[116:119]
	v_mfma_f32_16x16x32_bf16 v[112:115], v[180:183], v[196:199], v[112:115]
	v_mfma_f32_16x16x32_bf16 v[100:103], v[172:175], v[204:207], v[100:103]
	v_mfma_f32_16x16x32_bf16 v[96:99], v[180:183], v[204:207], v[96:99]
	v_mfma_f32_16x16x32_bf16 v[84:87], v[172:175], v[222:225], v[84:87]
	v_mfma_f32_16x16x32_bf16 v[80:83], v[180:183], v[222:225], v[80:83]
	s_setprio 0
	s_barrier
	s_add_i32 s74, s58, s3
	v_lshl_add_u64 v[158:159], s[42:43], 0, v[146:147]
	s_mov_b32 m0, s74
	ds_read_b128 v[184:187], v164 offset:16384
	ds_read_b128 v[188:191], v164 offset:17408
	ds_read_b128 v[192:195], v164 offset:18432
	ds_read_b128 v[196:199], v164 offset:19456
	ds_read_b128 v[200:203], v164 offset:20480
	ds_read_b128 v[204:207], v164 offset:21504
	ds_read_b128 v[218:221], v164 offset:22528
	ds_read_b128 v[222:225], v164 offset:23552
	global_load_lds_dwordx4 v[158:159], off
	s_add_i32 m0, s74, 0x2000
	s_add_u32 s74, s42, 0x40000
	v_lshl_add_u64 v[208:209], s[42:43], 0, v[144:145]
	s_addc_u32 s75, s43, 0
	s_add_i32 s81, s59, s3
	global_load_lds_dwordx4 v[208:209], off
	v_lshl_add_u64 v[226:227], s[74:75], 0, v[146:147]
	s_mov_b32 m0, s81
	v_lshl_add_u64 v[228:229], s[44:45], 0, v[144:145]
	global_load_lds_dwordx4 v[226:227], off
	v_lshl_add_u64 v[226:227], s[74:75], 0, v[144:145]
	s_add_i32 m0, s81, 0x2000
	s_nop 0
	global_load_lds_dwordx4 v[226:227], off
	v_lshl_add_u64 v[226:227], s[44:45], 0, v[146:147]
	s_mov_b32 m0, s21
	s_nop 0
	global_load_lds_dwordx4 v[226:227], off
	s_mov_b32 m0, s47
	s_nop 0
	global_load_lds_dwordx4 v[228:229], off
	s_waitcnt vmcnt(8)
	s_waitcnt lgkmcnt(0)
	s_barrier
	s_setprio 3
	s_waitcnt lgkmcnt(0)
	v_mfma_f32_16x16x32_bf16 v[76:79], v[32:35], v[184:187], v[76:79]
	v_mfma_f32_16x16x32_bf16 v[72:75], v[40:43], v[184:187], v[72:75]
	v_mfma_f32_16x16x32_bf16 v[60:63], v[32:35], v[192:195], v[60:63]
	v_mfma_f32_16x16x32_bf16 v[56:59], v[40:43], v[192:195], v[56:59]
	v_mfma_f32_16x16x32_bf16 v[28:31], v[32:35], v[200:203], v[28:31]
	v_mfma_f32_16x16x32_bf16 v[24:27], v[40:43], v[200:203], v[24:27]
	v_mfma_f32_16x16x32_bf16 v[12:15], v[32:35], v[218:221], v[12:15]
	v_mfma_f32_16x16x32_bf16 v[8:11], v[40:43], v[218:221], v[8:11]
	v_mfma_f32_16x16x32_bf16 v[76:79], v[36:39], v[188:191], v[76:79]
	v_mfma_f32_16x16x32_bf16 v[72:75], v[44:47], v[188:191], v[72:75]
	v_mfma_f32_16x16x32_bf16 v[60:63], v[36:39], v[196:199], v[60:63]
	v_mfma_f32_16x16x32_bf16 v[56:59], v[44:47], v[196:199], v[56:59]
	v_mfma_f32_16x16x32_bf16 v[28:31], v[36:39], v[204:207], v[28:31]
	v_mfma_f32_16x16x32_bf16 v[24:27], v[44:47], v[204:207], v[24:27]
	v_mfma_f32_16x16x32_bf16 v[12:15], v[36:39], v[222:225], v[12:15]
	v_mfma_f32_16x16x32_bf16 v[8:11], v[44:47], v[222:225], v[8:11]
	s_setprio 0
	s_setprio 3
	v_mfma_f32_16x16x32_bf16 v[20:23], v[168:171], v[200:203], v[20:23]
	v_mfma_f32_16x16x32_bf16 v[16:19], v[176:179], v[200:203], v[16:19]
	v_mfma_f32_16x16x32_bf16 v[4:7], v[168:171], v[218:221], v[4:7]
	v_mfma_f32_16x16x32_bf16 v[0:3], v[176:179], v[218:221], v[0:3]
	v_mfma_f32_16x16x32_bf16 v[32:35], v[168:171], v[184:187], v[68:71]
	v_mfma_f32_16x16x32_bf16 v[36:39], v[176:179], v[184:187], v[64:67]
	v_mfma_f32_16x16x32_bf16 v[40:43], v[168:171], v[192:195], v[52:55]
	v_mfma_f32_16x16x32_bf16 v[44:47], v[176:179], v[192:195], v[48:51]
	v_mfma_f32_16x16x32_bf16 v[20:23], v[172:175], v[204:207], v[20:23]
	v_mfma_f32_16x16x32_bf16 v[16:19], v[180:183], v[204:207], v[16:19]
	v_mfma_f32_16x16x32_bf16 v[4:7], v[172:175], v[222:225], v[4:7]
	v_mfma_f32_16x16x32_bf16 v[0:3], v[180:183], v[222:225], v[0:3]
	v_mfma_f32_16x16x32_bf16 v[32:35], v[172:175], v[188:191], v[32:35]
	v_mfma_f32_16x16x32_bf16 v[36:39], v[180:183], v[188:191], v[36:39]
	v_mfma_f32_16x16x32_bf16 v[40:43], v[172:175], v[196:199], v[40:43]
	v_mfma_f32_16x16x32_bf16 v[44:47], v[180:183], v[196:199], v[44:47]
	s_setprio 0
	s_barrier
	s_add_i32 s74, 0, 0x18000
	s_add_i32 s75, 0, 0x1c000
	v_add_u32_e32 v68, s74, v149
	v_add_u32_e32 v167, s75, v149
	ds_read_b128 v[48:51], v68
	ds_read_b128 v[52:55], v68 offset:1024
	ds_read_b128 v[64:67], v68 offset:2048
	ds_read_b128 v[68:71], v68 offset:3072
	ds_read_b128 v[168:171], v167
	ds_read_b128 v[172:175], v167 offset:1024
	ds_read_b128 v[176:179], v167 offset:2048
	ds_read_b128 v[180:183], v167 offset:3072
	s_add_u32 s44, s44, 0x40000
	s_addc_u32 s45, s45, 0
	s_mov_b32 m0, s48
	v_lshl_add_u64 v[230:231], s[44:45], 0, v[146:147]
	ds_read_b128 v[184:187], v164 offset:32768
	ds_read_b128 v[188:191], v164 offset:33792
	ds_read_b128 v[192:195], v164 offset:34816
	ds_read_b128 v[196:199], v164 offset:35840
	ds_read_b128 v[200:203], v164 offset:36864
	ds_read_b128 v[204:207], v164 offset:37888
	ds_read_b128 v[218:221], v164 offset:38912
	ds_read_b128 v[222:225], v164 offset:39936
	global_load_lds_dwordx4 v[230:231], off
	v_lshl_add_u64 v[230:231], s[44:45], 0, v[144:145]
	s_mov_b32 m0, s49
	s_nop 0
	global_load_lds_dwordx4 v[230:231], off
	s_waitcnt vmcnt(8)
	s_waitcnt lgkmcnt(0)
	s_barrier
	s_setprio 3
	s_waitcnt lgkmcnt(0)
	v_mfma_f32_16x16x32_bf16 v[140:143], v[48:51], v[184:187], v[140:143]
	v_mfma_f32_16x16x32_bf16 v[136:139], v[64:67], v[184:187], v[136:139]
	v_mfma_f32_16x16x32_bf16 v[124:127], v[48:51], v[192:195], v[124:127]
	v_mfma_f32_16x16x32_bf16 v[120:123], v[64:67], v[192:195], v[120:123]
	v_mfma_f32_16x16x32_bf16 v[108:111], v[48:51], v[200:203], v[108:111]
	v_mfma_f32_16x16x32_bf16 v[104:107], v[64:67], v[200:203], v[104:107]
	v_mfma_f32_16x16x32_bf16 v[92:95], v[48:51], v[218:221], v[92:95]
	v_mfma_f32_16x16x32_bf16 v[88:91], v[64:67], v[218:221], v[88:91]
	v_mfma_f32_16x16x32_bf16 v[140:143], v[52:55], v[188:191], v[140:143]
	v_mfma_f32_16x16x32_bf16 v[136:139], v[68:71], v[188:191], v[136:139]
	v_mfma_f32_16x16x32_bf16 v[124:127], v[52:55], v[196:199], v[124:127]
	v_mfma_f32_16x16x32_bf16 v[120:123], v[68:71], v[196:199], v[120:123]
	v_mfma_f32_16x16x32_bf16 v[108:111], v[52:55], v[204:207], v[108:111]
	v_mfma_f32_16x16x32_bf16 v[104:107], v[68:71], v[204:207], v[104:107]
	v_mfma_f32_16x16x32_bf16 v[92:95], v[52:55], v[222:225], v[92:95]
	v_mfma_f32_16x16x32_bf16 v[88:91], v[68:71], v[222:225], v[88:91]
	s_setprio 0
	s_setprio 3
	v_mfma_f32_16x16x32_bf16 v[132:135], v[168:171], v[184:187], v[132:135]
	v_mfma_f32_16x16x32_bf16 v[128:131], v[176:179], v[184:187], v[128:131]
	v_mfma_f32_16x16x32_bf16 v[116:119], v[168:171], v[192:195], v[116:119]
	v_mfma_f32_16x16x32_bf16 v[112:115], v[176:179], v[192:195], v[112:115]
	v_mfma_f32_16x16x32_bf16 v[100:103], v[168:171], v[200:203], v[100:103]
	v_mfma_f32_16x16x32_bf16 v[96:99], v[176:179], v[200:203], v[96:99]
	v_mfma_f32_16x16x32_bf16 v[84:87], v[168:171], v[218:221], v[84:87]
	v_mfma_f32_16x16x32_bf16 v[80:83], v[176:179], v[218:221], v[80:83]
	v_mfma_f32_16x16x32_bf16 v[132:135], v[172:175], v[188:191], v[132:135]
	v_mfma_f32_16x16x32_bf16 v[128:131], v[180:183], v[188:191], v[128:131]
	v_mfma_f32_16x16x32_bf16 v[116:119], v[172:175], v[196:199], v[116:119]
	v_mfma_f32_16x16x32_bf16 v[112:115], v[180:183], v[196:199], v[112:115]
	v_mfma_f32_16x16x32_bf16 v[100:103], v[172:175], v[204:207], v[100:103]
	v_mfma_f32_16x16x32_bf16 v[96:99], v[180:183], v[204:207], v[96:99]
	v_mfma_f32_16x16x32_bf16 v[84:87], v[172:175], v[222:225], v[84:87]
	v_mfma_f32_16x16x32_bf16 v[80:83], v[180:183], v[222:225], v[80:83]
	s_setprio 0
	s_barrier
	s_add_i32 s44, s74, s3
	v_lshl_add_u64 v[158:159], v[158:159], 0, s[10:11]
	s_mov_b32 m0, s44
	ds_read_b128 v[184:187], v164 offset:49152
	ds_read_b128 v[188:191], v164 offset:50176
	ds_read_b128 v[192:195], v164 offset:51200
	ds_read_b128 v[196:199], v164 offset:52224
	ds_read_b128 v[200:203], v164 offset:53248
	ds_read_b128 v[204:207], v164 offset:54272
	ds_read_b128 v[218:221], v164 offset:55296
	ds_read_b128 v[222:225], v164 offset:56320
	global_load_lds_dwordx4 v[158:159], off
	s_add_i32 m0, s44, 0x2000
	s_add_u32 s42, s42, 0x40080
	v_lshl_add_u64 v[158:159], v[208:209], 0, s[10:11]
	s_addc_u32 s43, s43, 0
	s_add_i32 s44, s75, s3
	global_load_lds_dwordx4 v[158:159], off
	v_lshl_add_u64 v[158:159], s[42:43], 0, v[146:147]
	s_mov_b32 m0, s44
	s_nop 0
	global_load_lds_dwordx4 v[158:159], off
	v_lshl_add_u64 v[158:159], s[42:43], 0, v[144:145]
	s_add_i32 m0, s44, 0x2000
	s_nop 0
	global_load_lds_dwordx4 v[158:159], off
	v_lshl_add_u64 v[158:159], v[226:227], 0, s[10:11]
	s_mov_b32 m0, s51
	s_nop 0
	global_load_lds_dwordx4 v[158:159], off
	v_lshl_add_u64 v[158:159], v[228:229], 0, s[10:11]
	s_mov_b32 m0, s52
	s_nop 0
	global_load_lds_dwordx4 v[158:159], off
	s_waitcnt vmcnt(8)
	s_waitcnt lgkmcnt(0)
	s_barrier
	s_setprio 3
	s_waitcnt lgkmcnt(0)
	v_mfma_f32_16x16x32_bf16 v[76:79], v[48:51], v[184:187], v[76:79]
	v_mfma_f32_16x16x32_bf16 v[72:75], v[64:67], v[184:187], v[72:75]
	v_mfma_f32_16x16x32_bf16 v[60:63], v[48:51], v[192:195], v[60:63]
	v_mfma_f32_16x16x32_bf16 v[56:59], v[64:67], v[192:195], v[56:59]
	v_mfma_f32_16x16x32_bf16 v[28:31], v[48:51], v[200:203], v[28:31]
	v_mfma_f32_16x16x32_bf16 v[24:27], v[64:67], v[200:203], v[24:27]
	v_mfma_f32_16x16x32_bf16 v[12:15], v[48:51], v[218:221], v[12:15]
	v_mfma_f32_16x16x32_bf16 v[8:11], v[64:67], v[218:221], v[8:11]
	v_mfma_f32_16x16x32_bf16 v[76:79], v[52:55], v[188:191], v[76:79]
	v_mfma_f32_16x16x32_bf16 v[72:75], v[68:71], v[188:191], v[72:75]
	v_mfma_f32_16x16x32_bf16 v[60:63], v[52:55], v[196:199], v[60:63]
	v_mfma_f32_16x16x32_bf16 v[56:59], v[68:71], v[196:199], v[56:59]
	v_mfma_f32_16x16x32_bf16 v[28:31], v[52:55], v[204:207], v[28:31]
	v_mfma_f32_16x16x32_bf16 v[24:27], v[68:71], v[204:207], v[24:27]
	v_mfma_f32_16x16x32_bf16 v[12:15], v[52:55], v[222:225], v[12:15]
	v_mfma_f32_16x16x32_bf16 v[8:11], v[68:71], v[222:225], v[8:11]
	s_setprio 0
	s_setprio 3
	v_mfma_f32_16x16x32_bf16 v[32:35], v[168:171], v[184:187], v[32:35]
	v_mfma_f32_16x16x32_bf16 v[68:71], v[172:175], v[188:191], v[32:35]
	v_mfma_f32_16x16x32_bf16 v[32:35], v[176:179], v[184:187], v[36:39]
	v_mfma_f32_16x16x32_bf16 v[64:67], v[180:183], v[188:191], v[32:35]
	v_mfma_f32_16x16x32_bf16 v[32:35], v[168:171], v[192:195], v[40:43]
	v_mfma_f32_16x16x32_bf16 v[52:55], v[172:175], v[196:199], v[32:35]
	v_mfma_f32_16x16x32_bf16 v[32:35], v[176:179], v[192:195], v[44:47]
	v_mfma_f32_16x16x32_bf16 v[20:23], v[168:171], v[200:203], v[20:23]
	v_mfma_f32_16x16x32_bf16 v[16:19], v[176:179], v[200:203], v[16:19]
	v_mfma_f32_16x16x32_bf16 v[4:7], v[168:171], v[218:221], v[4:7]
	v_mfma_f32_16x16x32_bf16 v[0:3], v[176:179], v[218:221], v[0:3]
	v_mfma_f32_16x16x32_bf16 v[48:51], v[180:183], v[196:199], v[32:35]
	v_mfma_f32_16x16x32_bf16 v[20:23], v[172:175], v[204:207], v[20:23]
	v_mfma_f32_16x16x32_bf16 v[16:19], v[180:183], v[204:207], v[16:19]
	v_mfma_f32_16x16x32_bf16 v[4:7], v[172:175], v[222:225], v[4:7]
	v_mfma_f32_16x16x32_bf16 v[0:3], v[180:183], v[222:225], v[0:3]
	s_setprio 0
	s_barrier
	s_add_i32 s73, s73, 2
	s_add_u32 s40, s40, 0x100
	s_addc_u32 s41, s41, 0
	s_add_u32 s71, s71, 0x100
	s_addc_u32 s72, s72, 0
	s_cmp_gt_u32 s73, 13
	s_cbranch_scc0 .LBB0_771
	s_and_b64 vcc, exec, s[12:13]
	s_cbranch_vccz .LBB0_774
	s_barrier

.LBB0_895:
	ds_read_b128 v[150:153], v144
	ds_read_b128 v[154:157], v144 offset:1024
	ds_read_b128 v[158:161], v144 offset:2048
	ds_read_b128 v[162:165], v144 offset:3072
	ds_read_b128 v[166:169], v145
	ds_read_b128 v[170:173], v145 offset:1024
	ds_read_b128 v[174:177], v145 offset:2048
	ds_read_b128 v[178:181], v145 offset:3072
	s_add_u32 s30, s28, 0xfffc0080
	s_addc_u32 s31, s29, -1
	s_cmp_eq_u32 s66, 12
	s_cselect_b32 s37, s19, s31
	s_cselect_b32 s36, s62, s30
	s_cselect_b32 s31, s17, s65
	s_cselect_b32 s30, s63, s64
	v_lshl_add_u64 v[220:221], s[28:29], 0, v[134:135]
	s_add_i32 m0, s27, 0xc000
	ds_read_b128 v[182:185], v146
	ds_read_b128 v[186:189], v146 offset:1024
	ds_read_b128 v[190:193], v146 offset:2048
	ds_read_b128 v[194:197], v146 offset:3072
	ds_read_b128 v[198:201], v146 offset:4096
	ds_read_b128 v[202:205], v146 offset:5120
	ds_read_b128 v[206:209], v146 offset:6144
	ds_read_b128 v[216:219], v146 offset:7168
	global_load_lds_dwordx4 v[220:221], off
	v_lshl_add_u64 v[220:221], s[28:29], 0, v[136:137]
	s_add_i32 m0, s27, 0xe000
	s_nop 0
	global_load_lds_dwordx4 v[220:221], off
	s_waitcnt vmcnt(8)
	s_waitcnt lgkmcnt(0)
	s_barrier
	s_setprio 3
	s_waitcnt lgkmcnt(0)
	v_mfma_f32_16x16x32_bf16 v[124:127], v[150:153], v[182:185], v[124:127]
	v_mfma_f32_16x16x32_bf16 v[120:123], v[158:161], v[182:185], v[120:123]
	v_mfma_f32_16x16x32_bf16 v[108:111], v[150:153], v[190:193], v[108:111]
	v_mfma_f32_16x16x32_bf16 v[104:107], v[158:161], v[190:193], v[104:107]
	v_mfma_f32_16x16x32_bf16 v[92:95], v[150:153], v[198:201], v[92:95]
	v_mfma_f32_16x16x32_bf16 v[88:91], v[158:161], v[198:201], v[88:91]
	v_mfma_f32_16x16x32_bf16 v[76:79], v[150:153], v[206:209], v[76:79]
	v_mfma_f32_16x16x32_bf16 v[72:75], v[158:161], v[206:209], v[72:75]
	v_mfma_f32_16x16x32_bf16 v[124:127], v[154:157], v[186:189], v[124:127]
	v_mfma_f32_16x16x32_bf16 v[120:123], v[162:165], v[186:189], v[120:123]
	v_mfma_f32_16x16x32_bf16 v[108:111], v[154:157], v[194:197], v[108:111]
	v_mfma_f32_16x16x32_bf16 v[104:107], v[162:165], v[194:197], v[104:107]
	v_mfma_f32_16x16x32_bf16 v[92:95], v[154:157], v[202:205], v[92:95]
	v_mfma_f32_16x16x32_bf16 v[88:91], v[162:165], v[202:205], v[88:91]
	v_mfma_f32_16x16x32_bf16 v[76:79], v[154:157], v[216:219], v[76:79]
	v_mfma_f32_16x16x32_bf16 v[72:75], v[162:165], v[216:219], v[72:75]
	s_setprio 0
	s_setprio 3
	v_mfma_f32_16x16x32_bf16 v[116:119], v[166:169], v[182:185], v[116:119]
	v_mfma_f32_16x16x32_bf16 v[112:115], v[174:177], v[182:185], v[112:115]
	v_mfma_f32_16x16x32_bf16 v[100:103], v[166:169], v[190:193], v[100:103]
	v_mfma_f32_16x16x32_bf16 v[96:99], v[174:177], v[190:193], v[96:99]
	v_mfma_f32_16x16x32_bf16 v[84:87], v[166:169], v[198:201], v[84:87]
	v_mfma_f32_16x16x32_bf16 v[80:83], v[174:177], v[198:201], v[80:83]
	v_mfma_f32_16x16x32_bf16 v[68:71], v[166:169], v[206:209], v[68:71]
	v_mfma_f32_16x16x32_bf16 v[64:67], v[174:177], v[206:209], v[64:67]
	v_mfma_f32_16x16x32_bf16 v[116:119], v[170:173], v[186:189], v[116:119]
	v_mfma_f32_16x16x32_bf16 v[112:115], v[178:181], v[186:189], v[112:115]
	v_mfma_f32_16x16x32_bf16 v[100:103], v[170:173], v[194:197], v[100:103]
	v_mfma_f32_16x16x32_bf16 v[96:99], v[178:181], v[194:197], v[96:99]
	v_mfma_f32_16x16x32_bf16 v[84:87], v[170:173], v[202:205], v[84:87]
	v_mfma_f32_16x16x32_bf16 v[80:83], v[178:181], v[202:205], v[80:83]
	v_mfma_f32_16x16x32_bf16 v[68:71], v[170:173], v[216:219], v[68:71]
	v_mfma_f32_16x16x32_bf16 v[64:67], v[178:181], v[216:219], v[64:67]
	s_setprio 0
	s_barrier
	s_add_i32 s67, s46, s3
	v_lshl_add_u64 v[220:221], s[30:31], 0, v[130:131]
	s_mov_b32 m0, s67
	ds_read_b128 v[182:185], v146 offset:16384
	ds_read_b128 v[186:189], v146 offset:17408
	ds_read_b128 v[190:193], v146 offset:18432
	ds_read_b128 v[194:197], v146 offset:19456
	ds_read_b128 v[198:201], v146 offset:20480
	ds_read_b128 v[202:205], v146 offset:21504
	ds_read_b128 v[206:209], v146 offset:22528
	ds_read_b128 v[216:219], v146 offset:23552
	global_load_lds_dwordx4 v[220:221], off
	s_add_i32 m0, s67, 0x2000
	s_add_u32 s68, s30, 0x40000
	v_lshl_add_u64 v[222:223], s[30:31], 0, v[128:129]
	s_addc_u32 s69, s31, 0
	s_add_i32 s67, s47, s3
	global_load_lds_dwordx4 v[222:223], off
	v_lshl_add_u64 v[224:225], s[68:69], 0, v[130:131]
	s_mov_b32 m0, s67
	v_lshl_add_u64 v[226:227], s[36:37], 0, v[128:129]
	global_load_lds_dwordx4 v[224:225], off
	v_lshl_add_u64 v[224:225], s[68:69], 0, v[128:129]
	s_add_i32 m0, s67, 0x2000
	s_nop 0
	global_load_lds_dwordx4 v[224:225], off
	v_lshl_add_u64 v[224:225], s[36:37], 0, v[130:131]
	s_mov_b32 m0, s27
	s_nop 0
	global_load_lds_dwordx4 v[224:225], off
	s_mov_b32 m0, s39
	s_nop 0
	global_load_lds_dwordx4 v[226:227], off
	s_waitcnt vmcnt(8)
	s_waitcnt lgkmcnt(0)
	s_barrier
	s_setprio 3
	s_waitcnt lgkmcnt(0)
	v_mfma_f32_16x16x32_bf16 v[60:63], v[150:153], v[182:185], v[60:63]
	v_mfma_f32_16x16x32_bf16 v[56:59], v[158:161], v[182:185], v[56:59]
	v_mfma_f32_16x16x32_bf16 v[44:47], v[150:153], v[190:193], v[44:47]
	v_mfma_f32_16x16x32_bf16 v[40:43], v[158:161], v[190:193], v[40:43]
	v_mfma_f32_16x16x32_bf16 v[28:31], v[150:153], v[198:201], v[28:31]
	v_mfma_f32_16x16x32_bf16 v[24:27], v[158:161], v[198:201], v[24:27]
	v_mfma_f32_16x16x32_bf16 v[12:15], v[150:153], v[206:209], v[12:15]
	v_mfma_f32_16x16x32_bf16 v[8:11], v[158:161], v[206:209], v[8:11]
	v_mfma_f32_16x16x32_bf16 v[60:63], v[154:157], v[186:189], v[60:63]
	v_mfma_f32_16x16x32_bf16 v[56:59], v[162:165], v[186:189], v[56:59]
	v_mfma_f32_16x16x32_bf16 v[44:47], v[154:157], v[194:197], v[44:47]
	v_mfma_f32_16x16x32_bf16 v[40:43], v[162:165], v[194:197], v[40:43]
	v_mfma_f32_16x16x32_bf16 v[28:31], v[154:157], v[202:205], v[28:31]
	v_mfma_f32_16x16x32_bf16 v[24:27], v[162:165], v[202:205], v[24:27]
	v_mfma_f32_16x16x32_bf16 v[12:15], v[154:157], v[216:219], v[12:15]
	v_mfma_f32_16x16x32_bf16 v[8:11], v[162:165], v[216:219], v[8:11]
	s_setprio 0
	s_setprio 3
	v_mfma_f32_16x16x32_bf16 v[52:55], v[166:169], v[182:185], v[52:55]
	v_mfma_f32_16x16x32_bf16 v[48:51], v[174:177], v[182:185], v[48:51]
	v_mfma_f32_16x16x32_bf16 v[36:39], v[166:169], v[190:193], v[36:39]
	v_mfma_f32_16x16x32_bf16 v[32:35], v[174:177], v[190:193], v[32:35]
	v_mfma_f32_16x16x32_bf16 v[20:23], v[166:169], v[198:201], v[20:23]
	v_mfma_f32_16x16x32_bf16 v[16:19], v[174:177], v[198:201], v[16:19]
	v_mfma_f32_16x16x32_bf16 v[4:7], v[166:169], v[206:209], v[4:7]
	v_mfma_f32_16x16x32_bf16 v[0:3], v[174:177], v[206:209], v[0:3]
	v_mfma_f32_16x16x32_bf16 v[52:55], v[170:173], v[186:189], v[52:55]
	v_mfma_f32_16x16x32_bf16 v[48:51], v[178:181], v[186:189], v[48:51]
	v_mfma_f32_16x16x32_bf16 v[36:39], v[170:173], v[194:197], v[36:39]
	v_mfma_f32_16x16x32_bf16 v[32:35], v[178:181], v[194:197], v[32:35]
	v_mfma_f32_16x16x32_bf16 v[20:23], v[170:173], v[202:205], v[20:23]
	v_mfma_f32_16x16x32_bf16 v[16:19], v[178:181], v[202:205], v[16:19]
	v_mfma_f32_16x16x32_bf16 v[4:7], v[170:173], v[216:219], v[4:7]
	v_mfma_f32_16x16x32_bf16 v[0:3], v[178:181], v[216:219], v[0:3]
	s_setprio 0
	s_barrier
	s_add_i32 s67, 0, 0x18000
	v_add_u32_e32 v149, s67, v142
	s_add_i32 s68, 0, 0x1c000
	ds_read_b128 v[150:153], v149
	ds_read_b128 v[154:157], v149 offset:1024
	ds_read_b128 v[158:161], v149 offset:2048
	ds_read_b128 v[162:165], v149 offset:3072
	v_add_u32_e32 v149, s68, v142
	ds_read_b128 v[166:169], v149
	ds_read_b128 v[170:173], v149 offset:1024
	ds_read_b128 v[174:177], v149 offset:2048
	ds_read_b128 v[178:181], v149 offset:3072
	s_add_u32 s36, s36, 0x40000
	s_addc_u32 s37, s37, 0
	s_mov_b32 m0, s40
	v_lshl_add_u64 v[228:229], s[36:37], 0, v[130:131]
	ds_read_b128 v[182:185], v146 offset:32768
	ds_read_b128 v[186:189], v146 offset:33792
	ds_read_b128 v[190:193], v146 offset:34816
	ds_read_b128 v[194:197], v146 offset:35840
	ds_read_b128 v[198:201], v146 offset:36864
	ds_read_b128 v[202:205], v146 offset:37888
	ds_read_b128 v[206:209], v146 offset:38912
	ds_read_b128 v[216:219], v146 offset:39936
	global_load_lds_dwordx4 v[228:229], off
	v_lshl_add_u64 v[228:229], s[36:37], 0, v[128:129]
	s_mov_b32 m0, s41
	s_nop 0
	global_load_lds_dwordx4 v[228:229], off
	s_waitcnt vmcnt(8)
	s_waitcnt lgkmcnt(0)
	s_barrier
	s_setprio 3
	s_waitcnt lgkmcnt(0)
	v_mfma_f32_16x16x32_bf16 v[124:127], v[150:153], v[182:185], v[124:127]
	v_mfma_f32_16x16x32_bf16 v[120:123], v[158:161], v[182:185], v[120:123]
	v_mfma_f32_16x16x32_bf16 v[108:111], v[150:153], v[190:193], v[108:111]
	v_mfma_f32_16x16x32_bf16 v[104:107], v[158:161], v[190:193], v[104:107]
	v_mfma_f32_16x16x32_bf16 v[92:95], v[150:153], v[198:201], v[92:95]
	v_mfma_f32_16x16x32_bf16 v[88:91], v[158:161], v[198:201], v[88:91]
	v_mfma_f32_16x16x32_bf16 v[76:79], v[150:153], v[206:209], v[76:79]
	v_mfma_f32_16x16x32_bf16 v[72:75], v[158:161], v[206:209], v[72:75]
	v_mfma_f32_16x16x32_bf16 v[124:127], v[154:157], v[186:189], v[124:127]
	v_mfma_f32_16x16x32_bf16 v[120:123], v[162:165], v[186:189], v[120:123]
	v_mfma_f32_16x16x32_bf16 v[108:111], v[154:157], v[194:197], v[108:111]
	v_mfma_f32_16x16x32_bf16 v[104:107], v[162:165], v[194:197], v[104:107]
	v_mfma_f32_16x16x32_bf16 v[92:95], v[154:157], v[202:205], v[92:95]
	v_mfma_f32_16x16x32_bf16 v[88:91], v[162:165], v[202:205], v[88:91]
	v_mfma_f32_16x16x32_bf16 v[76:79], v[154:157], v[216:219], v[76:79]
	v_mfma_f32_16x16x32_bf16 v[72:75], v[162:165], v[216:219], v[72:75]
	s_setprio 0
	s_setprio 3
	v_mfma_f32_16x16x32_bf16 v[116:119], v[166:169], v[182:185], v[116:119]
	v_mfma_f32_16x16x32_bf16 v[112:115], v[174:177], v[182:185], v[112:115]
	v_mfma_f32_16x16x32_bf16 v[100:103], v[166:169], v[190:193], v[100:103]
	v_mfma_f32_16x16x32_bf16 v[96:99], v[174:177], v[190:193], v[96:99]
	v_mfma_f32_16x16x32_bf16 v[84:87], v[166:169], v[198:201], v[84:87]
	v_mfma_f32_16x16x32_bf16 v[80:83], v[174:177], v[198:201], v[80:83]
	v_mfma_f32_16x16x32_bf16 v[68:71], v[166:169], v[206:209], v[68:71]
	v_mfma_f32_16x16x32_bf16 v[64:67], v[174:177], v[206:209], v[64:67]
	v_mfma_f32_16x16x32_bf16 v[116:119], v[170:173], v[186:189], v[116:119]
	v_mfma_f32_16x16x32_bf16 v[112:115], v[178:181], v[186:189], v[112:115]
	v_mfma_f32_16x16x32_bf16 v[100:103], v[170:173], v[194:197], v[100:103]
	v_mfma_f32_16x16x32_bf16 v[96:99], v[178:181], v[194:197], v[96:99]
	v_mfma_f32_16x16x32_bf16 v[84:87], v[170:173], v[202:205], v[84:87]
	v_mfma_f32_16x16x32_bf16 v[80:83], v[178:181], v[202:205], v[80:83]
	v_mfma_f32_16x16x32_bf16 v[68:71], v[170:173], v[216:219], v[68:71]
	v_mfma_f32_16x16x32_bf16 v[64:67], v[178:181], v[216:219], v[64:67]
	s_setprio 0
	s_barrier
	s_add_i32 s36, s67, s3
	v_lshl_add_u64 v[220:221], v[220:221], 0, s[12:13]
	s_mov_b32 m0, s36
	ds_read_b128 v[182:185], v146 offset:49152
	ds_read_b128 v[186:189], v146 offset:50176
	ds_read_b128 v[190:193], v146 offset:51200
	ds_read_b128 v[194:197], v146 offset:52224
	ds_read_b128 v[198:201], v146 offset:53248
	ds_read_b128 v[202:205], v146 offset:54272
	ds_read_b128 v[206:209], v146 offset:55296
	ds_read_b128 v[216:219], v146 offset:56320
	global_load_lds_dwordx4 v[220:221], off
	s_add_i32 m0, s36, 0x2000
	s_add_u32 s30, s30, 0x40080
	v_lshl_add_u64 v[220:221], v[222:223], 0, s[12:13]
	s_addc_u32 s31, s31, 0
	s_add_i32 s36, s68, s3
	global_load_lds_dwordx4 v[220:221], off
	v_lshl_add_u64 v[220:221], s[30:31], 0, v[130:131]
	s_mov_b32 m0, s36
	s_nop 0
	global_load_lds_dwordx4 v[220:221], off
	v_lshl_add_u64 v[220:221], s[30:31], 0, v[128:129]
	s_add_i32 m0, s36, 0x2000
	s_nop 0
	global_load_lds_dwordx4 v[220:221], off
	v_lshl_add_u64 v[220:221], v[224:225], 0, s[12:13]
	s_mov_b32 m0, s43
	s_nop 0
	global_load_lds_dwordx4 v[220:221], off
	v_lshl_add_u64 v[220:221], v[226:227], 0, s[12:13]
	s_mov_b32 m0, s44
	s_nop 0
	global_load_lds_dwordx4 v[220:221], off
	s_waitcnt vmcnt(8)
	s_waitcnt lgkmcnt(0)
	s_barrier
	s_setprio 3
	s_waitcnt lgkmcnt(0)
	v_mfma_f32_16x16x32_bf16 v[60:63], v[150:153], v[182:185], v[60:63]
	v_mfma_f32_16x16x32_bf16 v[56:59], v[158:161], v[182:185], v[56:59]
	v_mfma_f32_16x16x32_bf16 v[44:47], v[150:153], v[190:193], v[44:47]
	v_mfma_f32_16x16x32_bf16 v[40:43], v[158:161], v[190:193], v[40:43]
	v_mfma_f32_16x16x32_bf16 v[28:31], v[150:153], v[198:201], v[28:31]
	v_mfma_f32_16x16x32_bf16 v[24:27], v[158:161], v[198:201], v[24:27]
	v_mfma_f32_16x16x32_bf16 v[12:15], v[150:153], v[206:209], v[12:15]
	v_mfma_f32_16x16x32_bf16 v[8:11], v[158:161], v[206:209], v[8:11]
	v_mfma_f32_16x16x32_bf16 v[60:63], v[154:157], v[186:189], v[60:63]
	v_mfma_f32_16x16x32_bf16 v[56:59], v[162:165], v[186:189], v[56:59]
	v_mfma_f32_16x16x32_bf16 v[44:47], v[154:157], v[194:197], v[44:47]
	v_mfma_f32_16x16x32_bf16 v[40:43], v[162:165], v[194:197], v[40:43]
	v_mfma_f32_16x16x32_bf16 v[28:31], v[154:157], v[202:205], v[28:31]
	v_mfma_f32_16x16x32_bf16 v[24:27], v[162:165], v[202:205], v[24:27]
	v_mfma_f32_16x16x32_bf16 v[12:15], v[154:157], v[216:219], v[12:15]
	v_mfma_f32_16x16x32_bf16 v[8:11], v[162:165], v[216:219], v[8:11]
	s_setprio 0
	s_setprio 3
	v_mfma_f32_16x16x32_bf16 v[52:55], v[166:169], v[182:185], v[52:55]
	v_mfma_f32_16x16x32_bf16 v[48:51], v[174:177], v[182:185], v[48:51]
	v_mfma_f32_16x16x32_bf16 v[36:39], v[166:169], v[190:193], v[36:39]
	v_mfma_f32_16x16x32_bf16 v[32:35], v[174:177], v[190:193], v[32:35]
	v_mfma_f32_16x16x32_bf16 v[20:23], v[166:169], v[198:201], v[20:23]
	v_mfma_f32_16x16x32_bf16 v[16:19], v[174:177], v[198:201], v[16:19]
	v_mfma_f32_16x16x32_bf16 v[4:7], v[166:169], v[206:209], v[4:7]
	v_mfma_f32_16x16x32_bf16 v[0:3], v[174:177], v[206:209], v[0:3]
	v_mfma_f32_16x16x32_bf16 v[52:55], v[170:173], v[186:189], v[52:55]
	v_mfma_f32_16x16x32_bf16 v[48:51], v[178:181], v[186:189], v[48:51]
	v_mfma_f32_16x16x32_bf16 v[36:39], v[170:173], v[194:197], v[36:39]
	v_mfma_f32_16x16x32_bf16 v[32:35], v[178:181], v[194:197], v[32:35]
	v_mfma_f32_16x16x32_bf16 v[20:23], v[170:173], v[202:205], v[20:23]
	v_mfma_f32_16x16x32_bf16 v[16:19], v[178:181], v[202:205], v[16:19]
	v_mfma_f32_16x16x32_bf16 v[4:7], v[170:173], v[216:219], v[4:7]
	v_mfma_f32_16x16x32_bf16 v[0:3], v[178:181], v[216:219], v[0:3]
	s_setprio 0
	s_barrier
	s_add_i32 s66, s66, 2
	s_add_u32 s28, s28, 0x100
	s_addc_u32 s29, s29, 0
	s_add_u32 s64, s64, 0x100
	s_addc_u32 s65, s65, 0
	s_cmp_gt_u32 s66, 13
	s_cbranch_scc0 .LBB0_895
	s_and_b64 vcc, exec, s[14:15]
	s_cbranch_vccz .LBB0_898
	s_barrier

.LBB0_962:
	ds_read_b128 v[80:83], v164
	ds_read_b128 v[84:87], v164 offset:1024
	ds_read_b128 v[88:91], v164 offset:2048
	ds_read_b128 v[92:95], v164 offset:3072
	ds_read_b128 v[158:161], v165
	ds_read_b128 v[170:173], v165 offset:1024
	ds_read_b128 v[174:177], v165 offset:2048
	ds_read_b128 v[178:181], v165 offset:3072
	s_add_u32 s36, s30, 0xfff00080
	s_addc_u32 s37, s31, -1
	s_cmp_eq_u32 s70, s91
	s_cselect_b32 s39, s21, s37
	s_cselect_b32 s38, s66, s36
	s_cselect_b32 s37, s19, s69
	s_cselect_b32 s36, s67, s68
	v_lshl_add_u64 v[220:221], s[30:31], 0, v[150:151]
	s_add_i32 m0, s29, 0xc000
	ds_read_b128 v[182:185], v166
	ds_read_b128 v[186:189], v166 offset:1024
	ds_read_b128 v[190:193], v166 offset:2048
	ds_read_b128 v[194:197], v166 offset:3072
	ds_read_b128 v[198:201], v166 offset:4096
	ds_read_b128 v[202:205], v166 offset:5120
	ds_read_b128 v[206:209], v166 offset:6144
	ds_read_b128 v[216:219], v166 offset:7168
	global_load_lds_dwordx4 v[220:221], off
	v_lshl_add_u64 v[220:221], s[30:31], 0, v[152:153]
	s_add_i32 m0, s29, 0xe000
	s_nop 0
	global_load_lds_dwordx4 v[220:221], off
	s_waitcnt vmcnt(8)
	s_waitcnt lgkmcnt(0)
	s_barrier
	s_setprio 3
	s_waitcnt lgkmcnt(0)
	v_mfma_f32_16x16x32_bf16 v[140:143], v[80:83], v[182:185], v[140:143]
	v_mfma_f32_16x16x32_bf16 v[136:139], v[88:91], v[182:185], v[136:139]
	v_mfma_f32_16x16x32_bf16 v[124:127], v[80:83], v[190:193], v[124:127]
	v_mfma_f32_16x16x32_bf16 v[120:123], v[88:91], v[190:193], v[120:123]
	v_mfma_f32_16x16x32_bf16 v[108:111], v[80:83], v[198:201], v[108:111]
	v_mfma_f32_16x16x32_bf16 v[104:107], v[88:91], v[198:201], v[104:107]
	v_mfma_f32_16x16x32_bf16 v[76:79], v[80:83], v[206:209], v[76:79]
	v_mfma_f32_16x16x32_bf16 v[72:75], v[88:91], v[206:209], v[72:75]
	v_mfma_f32_16x16x32_bf16 v[140:143], v[84:87], v[186:189], v[140:143]
	v_mfma_f32_16x16x32_bf16 v[136:139], v[92:95], v[186:189], v[136:139]
	v_mfma_f32_16x16x32_bf16 v[124:127], v[84:87], v[194:197], v[124:127]
	v_mfma_f32_16x16x32_bf16 v[120:123], v[92:95], v[194:197], v[120:123]
	v_mfma_f32_16x16x32_bf16 v[108:111], v[84:87], v[202:205], v[108:111]
	v_mfma_f32_16x16x32_bf16 v[104:107], v[92:95], v[202:205], v[104:107]
	v_mfma_f32_16x16x32_bf16 v[76:79], v[84:87], v[216:219], v[76:79]
	v_mfma_f32_16x16x32_bf16 v[72:75], v[92:95], v[216:219], v[72:75]
	s_setprio 0
	s_setprio 3
	v_mfma_f32_16x16x32_bf16 v[132:135], v[158:161], v[182:185], v[132:135]
	v_mfma_f32_16x16x32_bf16 v[128:131], v[174:177], v[182:185], v[128:131]
	v_mfma_f32_16x16x32_bf16 v[116:119], v[158:161], v[190:193], v[116:119]
	v_mfma_f32_16x16x32_bf16 v[112:115], v[174:177], v[190:193], v[112:115]
	v_mfma_f32_16x16x32_bf16 v[100:103], v[158:161], v[198:201], v[100:103]
	v_mfma_f32_16x16x32_bf16 v[96:99], v[174:177], v[198:201], v[96:99]
	v_mfma_f32_16x16x32_bf16 v[68:71], v[158:161], v[206:209], v[68:71]
	v_mfma_f32_16x16x32_bf16 v[64:67], v[174:177], v[206:209], v[64:67]
	v_mfma_f32_16x16x32_bf16 v[132:135], v[170:173], v[186:189], v[132:135]
	v_mfma_f32_16x16x32_bf16 v[128:131], v[178:181], v[186:189], v[128:131]
	v_mfma_f32_16x16x32_bf16 v[116:119], v[170:173], v[194:197], v[116:119]
	v_mfma_f32_16x16x32_bf16 v[112:115], v[178:181], v[194:197], v[112:115]
	v_mfma_f32_16x16x32_bf16 v[100:103], v[170:173], v[202:205], v[100:103]
	v_mfma_f32_16x16x32_bf16 v[96:99], v[178:181], v[202:205], v[96:99]
	v_mfma_f32_16x16x32_bf16 v[68:71], v[170:173], v[216:219], v[68:71]
	v_mfma_f32_16x16x32_bf16 v[64:67], v[178:181], v[216:219], v[64:67]
	s_setprio 0
	s_barrier
	s_add_i32 s71, s53, s3
	v_lshl_add_u64 v[220:221], s[36:37], 0, v[146:147]
	s_mov_b32 m0, s71
	ds_read_b128 v[182:185], v166 offset:16384
	ds_read_b128 v[186:189], v166 offset:17408
	ds_read_b128 v[190:193], v166 offset:18432
	ds_read_b128 v[194:197], v166 offset:19456
	ds_read_b128 v[198:201], v166 offset:20480
	ds_read_b128 v[202:205], v166 offset:21504
	ds_read_b128 v[206:209], v166 offset:22528
	ds_read_b128 v[216:219], v166 offset:23552
	global_load_lds_dwordx4 v[220:221], off
	s_add_i32 m0, s71, 0x2000
	s_add_u32 s72, s36, 0x100000
	v_lshl_add_u64 v[222:223], s[36:37], 0, v[144:145]
	s_addc_u32 s73, s37, 0
	s_add_i32 s71, s54, s3
	global_load_lds_dwordx4 v[222:223], off
	v_lshl_add_u64 v[224:225], s[72:73], 0, v[146:147]
	s_mov_b32 m0, s71
	v_lshl_add_u64 v[226:227], s[38:39], 0, v[144:145]
	global_load_lds_dwordx4 v[224:225], off
	v_lshl_add_u64 v[224:225], s[72:73], 0, v[144:145]
	s_add_i32 m0, s71, 0x2000
	s_nop 0
	global_load_lds_dwordx4 v[224:225], off
	v_lshl_add_u64 v[224:225], s[38:39], 0, v[146:147]
	s_mov_b32 m0, s29
	s_nop 0
	global_load_lds_dwordx4 v[224:225], off
	s_mov_b32 m0, s41
	s_nop 0
	global_load_lds_dwordx4 v[226:227], off
	s_waitcnt vmcnt(8)
	s_waitcnt lgkmcnt(0)
	s_barrier
	s_setprio 3
	s_waitcnt lgkmcnt(0)
	v_mfma_f32_16x16x32_bf16 v[60:63], v[80:83], v[182:185], v[60:63]
	v_mfma_f32_16x16x32_bf16 v[56:59], v[88:91], v[182:185], v[56:59]
	v_mfma_f32_16x16x32_bf16 v[44:47], v[80:83], v[190:193], v[44:47]
	v_mfma_f32_16x16x32_bf16 v[40:43], v[88:91], v[190:193], v[40:43]
	v_mfma_f32_16x16x32_bf16 v[28:31], v[80:83], v[198:201], v[28:31]
	v_mfma_f32_16x16x32_bf16 v[24:27], v[88:91], v[198:201], v[24:27]
	v_mfma_f32_16x16x32_bf16 v[12:15], v[80:83], v[206:209], v[12:15]
	v_mfma_f32_16x16x32_bf16 v[8:11], v[88:91], v[206:209], v[8:11]
	v_mfma_f32_16x16x32_bf16 v[60:63], v[84:87], v[186:189], v[60:63]
	v_mfma_f32_16x16x32_bf16 v[56:59], v[92:95], v[186:189], v[56:59]
	v_mfma_f32_16x16x32_bf16 v[44:47], v[84:87], v[194:197], v[44:47]
	v_mfma_f32_16x16x32_bf16 v[40:43], v[92:95], v[194:197], v[40:43]
	v_mfma_f32_16x16x32_bf16 v[28:31], v[84:87], v[202:205], v[28:31]
	v_mfma_f32_16x16x32_bf16 v[24:27], v[92:95], v[202:205], v[24:27]
	v_mfma_f32_16x16x32_bf16 v[12:15], v[84:87], v[216:219], v[12:15]
	v_mfma_f32_16x16x32_bf16 v[8:11], v[92:95], v[216:219], v[8:11]
	s_setprio 0
	s_setprio 3
	v_mfma_f32_16x16x32_bf16 v[52:55], v[158:161], v[182:185], v[52:55]
	v_mfma_f32_16x16x32_bf16 v[48:51], v[174:177], v[182:185], v[48:51]
	v_mfma_f32_16x16x32_bf16 v[36:39], v[158:161], v[190:193], v[36:39]
	v_mfma_f32_16x16x32_bf16 v[32:35], v[174:177], v[190:193], v[32:35]
	v_mfma_f32_16x16x32_bf16 v[20:23], v[158:161], v[198:201], v[20:23]
	v_mfma_f32_16x16x32_bf16 v[16:19], v[174:177], v[198:201], v[16:19]
	v_mfma_f32_16x16x32_bf16 v[4:7], v[158:161], v[206:209], v[4:7]
	v_mfma_f32_16x16x32_bf16 v[0:3], v[174:177], v[206:209], v[0:3]
	v_mfma_f32_16x16x32_bf16 v[52:55], v[170:173], v[186:189], v[52:55]
	v_mfma_f32_16x16x32_bf16 v[48:51], v[178:181], v[186:189], v[48:51]
	v_mfma_f32_16x16x32_bf16 v[36:39], v[170:173], v[194:197], v[36:39]
	v_mfma_f32_16x16x32_bf16 v[32:35], v[178:181], v[194:197], v[32:35]
	v_mfma_f32_16x16x32_bf16 v[20:23], v[170:173], v[202:205], v[20:23]
	v_mfma_f32_16x16x32_bf16 v[16:19], v[178:181], v[202:205], v[16:19]
	v_mfma_f32_16x16x32_bf16 v[4:7], v[170:173], v[216:219], v[4:7]
	v_mfma_f32_16x16x32_bf16 v[0:3], v[178:181], v[216:219], v[0:3]
	s_setprio 0
	s_barrier
	s_add_i32 s71, 0, 0x18000
	s_add_i32 s72, 0, 0x1c000
	v_add_u32_e32 v92, s71, v149
	v_add_u32_e32 v169, s72, v149
	ds_read_b128 v[80:83], v92
	ds_read_b128 v[84:87], v92 offset:1024
	ds_read_b128 v[88:91], v92 offset:2048
	ds_read_b128 v[92:95], v92 offset:3072
	ds_read_b128 v[158:161], v169
	ds_read_b128 v[170:173], v169 offset:1024
	ds_read_b128 v[174:177], v169 offset:2048
	ds_read_b128 v[178:181], v169 offset:3072
	s_add_u32 s38, s38, 0x100000
	s_addc_u32 s39, s39, 0
	s_mov_b32 m0, s42
	v_lshl_add_u64 v[228:229], s[38:39], 0, v[146:147]
	ds_read_b128 v[182:185], v166 offset:32768
	ds_read_b128 v[186:189], v166 offset:33792
	ds_read_b128 v[190:193], v166 offset:34816
	ds_read_b128 v[194:197], v166 offset:35840
	ds_read_b128 v[198:201], v166 offset:36864
	ds_read_b128 v[202:205], v166 offset:37888
	ds_read_b128 v[206:209], v166 offset:38912
	ds_read_b128 v[216:219], v166 offset:39936
	global_load_lds_dwordx4 v[228:229], off
	v_lshl_add_u64 v[228:229], s[38:39], 0, v[144:145]
	s_mov_b32 m0, s43
	s_nop 0
	global_load_lds_dwordx4 v[228:229], off
	s_waitcnt vmcnt(8)
	s_waitcnt lgkmcnt(0)
	s_barrier
	s_setprio 3
	s_waitcnt lgkmcnt(0)
	v_mfma_f32_16x16x32_bf16 v[140:143], v[80:83], v[182:185], v[140:143]
	v_mfma_f32_16x16x32_bf16 v[136:139], v[88:91], v[182:185], v[136:139]
	v_mfma_f32_16x16x32_bf16 v[124:127], v[80:83], v[190:193], v[124:127]
	v_mfma_f32_16x16x32_bf16 v[120:123], v[88:91], v[190:193], v[120:123]
	v_mfma_f32_16x16x32_bf16 v[108:111], v[80:83], v[198:201], v[108:111]
	v_mfma_f32_16x16x32_bf16 v[104:107], v[88:91], v[198:201], v[104:107]
	v_mfma_f32_16x16x32_bf16 v[76:79], v[80:83], v[206:209], v[76:79]
	v_mfma_f32_16x16x32_bf16 v[72:75], v[88:91], v[206:209], v[72:75]
	v_mfma_f32_16x16x32_bf16 v[140:143], v[84:87], v[186:189], v[140:143]
	v_mfma_f32_16x16x32_bf16 v[136:139], v[92:95], v[186:189], v[136:139]
	v_mfma_f32_16x16x32_bf16 v[124:127], v[84:87], v[194:197], v[124:127]
	v_mfma_f32_16x16x32_bf16 v[120:123], v[92:95], v[194:197], v[120:123]
	v_mfma_f32_16x16x32_bf16 v[108:111], v[84:87], v[202:205], v[108:111]
	v_mfma_f32_16x16x32_bf16 v[104:107], v[92:95], v[202:205], v[104:107]
	v_mfma_f32_16x16x32_bf16 v[76:79], v[84:87], v[216:219], v[76:79]
	v_mfma_f32_16x16x32_bf16 v[72:75], v[92:95], v[216:219], v[72:75]
	s_setprio 0
	s_setprio 3
	v_mfma_f32_16x16x32_bf16 v[132:135], v[158:161], v[182:185], v[132:135]
	v_mfma_f32_16x16x32_bf16 v[128:131], v[174:177], v[182:185], v[128:131]
	v_mfma_f32_16x16x32_bf16 v[116:119], v[158:161], v[190:193], v[116:119]
	v_mfma_f32_16x16x32_bf16 v[112:115], v[174:177], v[190:193], v[112:115]
	v_mfma_f32_16x16x32_bf16 v[100:103], v[158:161], v[198:201], v[100:103]
	v_mfma_f32_16x16x32_bf16 v[96:99], v[174:177], v[198:201], v[96:99]
	v_mfma_f32_16x16x32_bf16 v[68:71], v[158:161], v[206:209], v[68:71]
	v_mfma_f32_16x16x32_bf16 v[64:67], v[174:177], v[206:209], v[64:67]
	v_mfma_f32_16x16x32_bf16 v[132:135], v[170:173], v[186:189], v[132:135]
	v_mfma_f32_16x16x32_bf16 v[128:131], v[178:181], v[186:189], v[128:131]
	v_mfma_f32_16x16x32_bf16 v[116:119], v[170:173], v[194:197], v[116:119]
	v_mfma_f32_16x16x32_bf16 v[112:115], v[178:181], v[194:197], v[112:115]
	v_mfma_f32_16x16x32_bf16 v[100:103], v[170:173], v[202:205], v[100:103]
	v_mfma_f32_16x16x32_bf16 v[96:99], v[178:181], v[202:205], v[96:99]
	v_mfma_f32_16x16x32_bf16 v[68:71], v[170:173], v[216:219], v[68:71]
	v_mfma_f32_16x16x32_bf16 v[64:67], v[178:181], v[216:219], v[64:67]
	s_setprio 0
	s_barrier
	s_add_i32 s38, s71, s3
	v_lshl_add_u64 v[220:221], v[220:221], 0, s[12:13]
	s_mov_b32 m0, s38
	ds_read_b128 v[182:185], v166 offset:49152
	ds_read_b128 v[186:189], v166 offset:50176
	ds_read_b128 v[190:193], v166 offset:51200
	ds_read_b128 v[194:197], v166 offset:52224
	ds_read_b128 v[198:201], v166 offset:53248
	ds_read_b128 v[202:205], v166 offset:54272
	ds_read_b128 v[206:209], v166 offset:55296
	ds_read_b128 v[216:219], v166 offset:56320
	global_load_lds_dwordx4 v[220:221], off
	s_add_i32 m0, s38, 0x2000
	s_add_u32 s36, s36, 0x100080
	v_lshl_add_u64 v[220:221], v[222:223], 0, s[12:13]
	s_addc_u32 s37, s37, 0
	s_add_i32 s38, s72, s3
	global_load_lds_dwordx4 v[220:221], off
	v_lshl_add_u64 v[220:221], s[36:37], 0, v[146:147]
	s_mov_b32 m0, s38
	s_nop 0
	global_load_lds_dwordx4 v[220:221], off
	v_lshl_add_u64 v[220:221], s[36:37], 0, v[144:145]
	s_add_i32 m0, s38, 0x2000
	s_nop 0
	global_load_lds_dwordx4 v[220:221], off
	v_lshl_add_u64 v[220:221], v[224:225], 0, s[12:13]
	s_mov_b32 m0, s47
	s_nop 0
	global_load_lds_dwordx4 v[220:221], off
	v_lshl_add_u64 v[220:221], v[226:227], 0, s[12:13]
	s_mov_b32 m0, s48
	s_nop 0
	global_load_lds_dwordx4 v[220:221], off
	s_waitcnt vmcnt(8)
	s_waitcnt lgkmcnt(0)
	s_barrier
	s_setprio 3
	s_waitcnt lgkmcnt(0)
	v_mfma_f32_16x16x32_bf16 v[60:63], v[80:83], v[182:185], v[60:63]
	v_mfma_f32_16x16x32_bf16 v[56:59], v[88:91], v[182:185], v[56:59]
	v_mfma_f32_16x16x32_bf16 v[44:47], v[80:83], v[190:193], v[44:47]
	v_mfma_f32_16x16x32_bf16 v[40:43], v[88:91], v[190:193], v[40:43]
	v_mfma_f32_16x16x32_bf16 v[28:31], v[80:83], v[198:201], v[28:31]
	v_mfma_f32_16x16x32_bf16 v[24:27], v[88:91], v[198:201], v[24:27]
	v_mfma_f32_16x16x32_bf16 v[12:15], v[80:83], v[206:209], v[12:15]
	v_mfma_f32_16x16x32_bf16 v[8:11], v[88:91], v[206:209], v[8:11]
	v_mfma_f32_16x16x32_bf16 v[60:63], v[84:87], v[186:189], v[60:63]
	v_mfma_f32_16x16x32_bf16 v[56:59], v[92:95], v[186:189], v[56:59]
	v_mfma_f32_16x16x32_bf16 v[44:47], v[84:87], v[194:197], v[44:47]
	v_mfma_f32_16x16x32_bf16 v[40:43], v[92:95], v[194:197], v[40:43]
	v_mfma_f32_16x16x32_bf16 v[28:31], v[84:87], v[202:205], v[28:31]
	v_mfma_f32_16x16x32_bf16 v[24:27], v[92:95], v[202:205], v[24:27]
	v_mfma_f32_16x16x32_bf16 v[12:15], v[84:87], v[216:219], v[12:15]
	v_mfma_f32_16x16x32_bf16 v[8:11], v[92:95], v[216:219], v[8:11]
	s_setprio 0
	s_setprio 3
	v_mfma_f32_16x16x32_bf16 v[52:55], v[158:161], v[182:185], v[52:55]
	v_mfma_f32_16x16x32_bf16 v[48:51], v[174:177], v[182:185], v[48:51]
	v_mfma_f32_16x16x32_bf16 v[36:39], v[158:161], v[190:193], v[36:39]
	v_mfma_f32_16x16x32_bf16 v[32:35], v[174:177], v[190:193], v[32:35]
	v_mfma_f32_16x16x32_bf16 v[20:23], v[158:161], v[198:201], v[20:23]
	v_mfma_f32_16x16x32_bf16 v[16:19], v[174:177], v[198:201], v[16:19]
	v_mfma_f32_16x16x32_bf16 v[4:7], v[158:161], v[206:209], v[4:7]
	v_mfma_f32_16x16x32_bf16 v[0:3], v[174:177], v[206:209], v[0:3]
	v_mfma_f32_16x16x32_bf16 v[52:55], v[170:173], v[186:189], v[52:55]
	v_mfma_f32_16x16x32_bf16 v[48:51], v[178:181], v[186:189], v[48:51]
	v_mfma_f32_16x16x32_bf16 v[36:39], v[170:173], v[194:197], v[36:39]
	v_mfma_f32_16x16x32_bf16 v[32:35], v[178:181], v[194:197], v[32:35]
	v_mfma_f32_16x16x32_bf16 v[20:23], v[170:173], v[202:205], v[20:23]
	v_mfma_f32_16x16x32_bf16 v[16:19], v[178:181], v[202:205], v[16:19]
	v_mfma_f32_16x16x32_bf16 v[4:7], v[170:173], v[216:219], v[4:7]
	v_mfma_f32_16x16x32_bf16 v[0:3], v[178:181], v[216:219], v[0:3]
	s_setprio 0
	s_barrier
	s_add_i32 s70, s70, 2
	s_add_u32 s30, s30, 0x100
	s_addc_u32 s31, s31, 0
	s_add_u32 s68, s68, 0x100
	s_addc_u32 s69, s69, 0
	s_cmp_gt_u32 s70, s97
	s_cbranch_scc0 .LBB0_962
	s_and_b64 vcc, exec, s[14:15]
	s_cbranch_vccz .LBB0_965
	s_barrier
